# scan: the per-step v scalar of two consecutive steps fetched with one ds_read2st64_b32 (half an LDS instruction less per step)
# speedup vs baseline: 1.0194x; 1.0034x over previous
; #define LAS __attribute__((address_space(3)))
; DI void scan_item(PP p, int l, int item, LAS unsigned char* lds) {
;     ...
;     for (int c = 0; c < NCH; ++c) {
;         if (wid >= 4) { if (c + 1 < NCH) { fill(c + 1); if (c + 2 < NCH) gl(c + 2); } }
;         else {
;             const LAS float* sp = buf + ((c & 1) * T) * 384;
;             f32x4 Ar0, Ar1, Aw0, Aw1, Ak0, Ak1, Aa0, Aa1, Ab0, Ab1; float Avv;
;             f32x4 Br0, Br1, Bw0, Bw1, Bk0, Bk1, Ba0, Ba1, Bb0, Bb1; float Bvv;
;             SC_LD(A, sp);
;             const ptrdiff_t ystep = dir ? -512 : 512;
;             u16* Yl = Yp + (size_t)steprow(b, dir, c * T) * 512 + (ptrdiff_t)ks * ystep;
; #pragma nounroll
;             for (int st = 0; st < T; st += 2) {
;                 SC_LD(B, sp + (st + 1) * 384);
;                 SC_STEP(A, st);
;                 if (st + 2 < T) SC_LD(A, sp + (st + 2) * 384);
.LBB0_253:
	s_mov_b64 s[6:7], -1
	s_and_b64 vcc, exec, s[44:45]
	s_cbranch_vccz .LBB0_265
	s_setprio 3
	s_lshl_b32 s7, s30, 5
	s_and_b32 s6, s7, 32
	s_mulk_i32 s6, 0x600
	v_lshl_add_u32 v154, v138, 2, s6
	v_lshl_add_u32 v153, v136, 2, s6
	ds_read_b128 v[0:3], v154 offset:0
	ds_read_b128 v[4:7], v154 offset:16
	ds_read_b128 v[24:27], v154 offset:768
	ds_read_b128 v[28:31], v154 offset:784
	ds_read_b128 v[16:19], v154 offset:512
	ds_read_b128 v[20:23], v154 offset:528
	ds_read_b128 v[32:35], v154 offset:1024
	ds_read_b128 v[36:39], v154 offset:1040
	ds_read2st64_b32 v[92:93], v153 offset0:5 offset1:11
	s_cmp_gt_u32 s30, 7
	s_cbranch_scc0 .Lscan_ctx_rows
	s_add_i32 s6, s7, 0xffffff00
	s_sub_i32 s68, 0x8ff, s7
	s_and_b64 s[8:9], s[46:47], exec
	s_cselect_b32 s6, s6, s68
	s_add_i32 s6, s6, s53
	s_branch .Lscan_row_done

; #define LAS __attribute__((address_space(3)))
; DI unsigned pack2(float lo, float hi) { f32x2 v = {lo, hi}; return __builtin_bit_cast(unsigned, __builtin_convertvector(v, bf16x2_t)); }
; DI void scan_item(PP p, int l, int item, LAS unsigned char* lds) {
;     ...
;     for (int c = 0; c < NCH; ++c) {
;         if (wid >= 4) { if (c + 1 < NCH) { fill(c + 1); if (c + 2 < NCH) gl(c + 2); } }
;         else {
;             const LAS float* sp = buf + ((c & 1) * T) * 384;
;             f32x4 Ar0, Ar1, Aw0, Aw1, Ak0, Ak1, Aa0, Aa1, Ab0, Ab1; float Avv;
;             f32x4 Br0, Br1, Bw0, Bw1, Bk0, Bk1, Ba0, Ba1, Bb0, Bb1; float Bvv;
;             SC_LD(A, sp);
;             const ptrdiff_t ystep = dir ? -512 : 512;
;             u16* Yl = Yp + (size_t)steprow(b, dir, c * T) * 512 + (ptrdiff_t)ks * ystep;
; #pragma nounroll
;             for (int st = 0; st < T; st += 2) {
;                 SC_LD(B, sp + (st + 1) * 384);
;                 SC_STEP(A, st);
;                 if (st + 2 < T) SC_LD(A, sp + (st + 2) * 384);
;                 SC_STEP(B, st + 1);
;                 if ((st & 6) == 6) {
;                     const LAS float* rp = ypl + (ks * 68 - lane) + (lane & ~7);
;                     const f32x4 q0 = *(const LAS f32x4*)rp, q1 = *(const LAS f32x4*)(rp + 4);
;                     Yl[(ptrdiff_t)(st - 6) * ystep] = (u16)(pack2(((q0[0] + q0[1]) + (q0[2] + q0[3])) + ((q1[0] + q1[1]) + (q1[2] + q1[3])), 0.f) & 0xffffu);
;                 }
;             }
.Lscan_row_done:
	s_ashr_i32 s7, s6, 31
	s_lshl_b64 s[6:7], s[6:7], 10
	v_lshl_add_u64 v[118:119], v[80:81], 0, s[6:7]
	s_lshl_b32 s8, s41, 4
	s_mov_b32 s9, s31
	v_mov_b32_e32 v126, v144
	v_mov_b32_e32 v127, v145
	v_mov_b32_e32 v124, v146
	v_mov_b32_e32 v125, v147
	v_mov_b32_e32 v122, v148
	v_mov_b32_e32 v123, v149
	v_mov_b32_e32 v120, v150
	v_mov_b32_e32 v121, v151
	ds_read_b128 v[40:43], v154 offset:1536
	ds_read_b128 v[44:47], v154 offset:1552
	ds_read_b128 v[64:67], v154 offset:2304
	ds_read_b128 v[68:71], v154 offset:2320
	ds_read_b128 v[56:59], v154 offset:2048
	ds_read_b128 v[60:63], v154 offset:2064
	ds_read_b128 v[72:75], v154 offset:2560
	ds_read_b128 v[76:79], v154 offset:2576
	s_waitcnt lgkmcnt(8)
	v_pk_mul_f32 v[156:157], v[24:25], v[126:127]
	v_pk_mul_f32 v[90:91], v[28:29], v[122:123]
	v_pk_fma_f32 v[126:127], v[92:93], v[16:17], v[126:127] op_sel_hi:[0,1,1]
	v_pk_fma_f32 v[156:157], v[124:125], v[26:27], v[156:157]
	v_pk_fma_f32 v[90:91], v[120:121], v[30:31], v[90:91]
	v_pk_fma_f32 v[124:125], v[92:93], v[18:19], v[124:125] op_sel_hi:[0,1,1]
	v_pk_fma_f32 v[122:123], v[92:93], v[20:21], v[122:123] op_sel_hi:[0,1,1]
	v_pk_add_f32 v[156:157], v[156:157], v[90:91]
	v_pk_fma_f32 v[120:121], v[92:93], v[22:23], v[120:121] op_sel_hi:[0,1,1]
	v_add_f32_e32 v155, v156, v157
	s_nop 1
	v_add_f32_dpp v155, v155, v155 quad_perm:[1,0,3,2] row_mask:0xf bank_mask:0xf bound_ctrl:1
	s_nop 1
	v_add_f32_dpp v155, v155, v155 quad_perm:[2,3,0,1] row_mask:0xf bank_mask:0xf bound_ctrl:1
	s_nop 1
	v_add_f32_dpp v156, v155, v155 row_half_mirror row_mask:0xf bank_mask:0xf bound_ctrl:1
	v_pk_fma_f32 v[126:127], v[156:157], v[32:33], v[126:127] op_sel_hi:[0,1,1]
	v_pk_fma_f32 v[124:125], v[156:157], v[34:35], v[124:125] op_sel_hi:[0,1,1]
	v_pk_fma_f32 v[122:123], v[156:157], v[36:37], v[122:123] op_sel_hi:[0,1,1]
	v_pk_fma_f32 v[120:121], v[156:157], v[38:39], v[120:121] op_sel_hi:[0,1,1]
	ds_read_b128 v[24:27], v154 offset:3840
	ds_read_b128 v[28:31], v154 offset:3856
	ds_read_b128 v[16:19], v154 offset:3584
	ds_read_b128 v[20:23], v154 offset:3600
	ds_read_b128 v[32:35], v154 offset:4096
	ds_read_b128 v[36:39], v154 offset:4112
	ds_read2st64_b32 v[98:99], v153 offset0:17 offset1:23
	s_waitcnt lgkmcnt(7)
	v_pk_mul_f32 v[156:157], v[64:65], v[126:127]
	v_pk_mul_f32 v[90:91], v[68:69], v[122:123]
	v_pk_mul_f32 v[158:159], v[0:1], v[126:127]
	v_pk_fma_f32 v[156:157], v[124:125], v[66:67], v[156:157]
	v_pk_fma_f32 v[90:91], v[120:121], v[70:71], v[90:91]
	v_pk_fma_f32 v[158:159], v[124:125], v[2:3], v[158:159]
	v_pk_fma_f32 v[126:127], v[92:93], v[56:57], v[126:127] op_sel:[1,0,0] op_sel_hi:[1,1,1]
	v_pk_fma_f32 v[158:159], v[122:123], v[4:5], v[158:159]
	v_pk_fma_f32 v[124:125], v[92:93], v[58:59], v[124:125] op_sel:[1,0,0] op_sel_hi:[1,1,1]
	v_pk_add_f32 v[156:157], v[156:157], v[90:91]
	v_pk_fma_f32 v[158:159], v[120:121], v[6:7], v[158:159]
	v_add_f32_e32 v155, v156, v157
	v_pk_fma_f32 v[122:123], v[92:93], v[60:61], v[122:123] op_sel:[1,0,0] op_sel_hi:[1,1,1]
	v_pk_fma_f32 v[120:121], v[92:93], v[62:63], v[120:121] op_sel:[1,0,0] op_sel_hi:[1,1,1]
	ds_read_b128 v[0:3], v154 offset:3072
	ds_read_b128 v[4:7], v154 offset:3088
	v_add_f32_e32 v158, v158, v159
	v_add_f32_dpp v155, v155, v155 quad_perm:[1,0,3,2] row_mask:0xf bank_mask:0xf bound_ctrl:1
	s_mov_b32 s6, 0x1010101
	s_mov_b32 s7, 0x1010101
	v_add_f32_dpp v158, v158, v158 quad_perm:[1,0,3,2] row_mask:0xf bank_mask:0xf bound_ctrl:1
	v_add_f32_dpp v155, v155, v155 quad_perm:[2,3,0,1] row_mask:0xf bank_mask:0xf bound_ctrl:1
	s_nop 0
	v_add_f32_dpp v158, v158, v158 quad_perm:[2,3,0,1] row_mask:0xf bank_mask:0xf bound_ctrl:1
	v_add_f32_dpp v156, v155, v155 row_half_mirror row_mask:0xf bank_mask:0xf bound_ctrl:1
	v_pk_fma_f32 v[126:127], v[156:157], v[72:73], v[126:127] op_sel_hi:[0,1,1]
	v_pk_fma_f32 v[124:125], v[156:157], v[74:75], v[124:125] op_sel_hi:[0,1,1]
	v_add_f32_dpp v158, v158, v158 row_half_mirror row_mask:0xf bank_mask:0xf bound_ctrl:1
	v_pk_fma_f32 v[122:123], v[156:157], v[76:77], v[122:123] op_sel_hi:[0,1,1]
	v_pk_fma_f32 v[120:121], v[156:157], v[78:79], v[120:121] op_sel_hi:[0,1,1]
	v_cndmask_b32_e64 v94, v94, v158, s[6:7]
	ds_read_b128 v[64:67], v154 offset:5376
	ds_read_b128 v[68:71], v154 offset:5392
	ds_read_b128 v[56:59], v154 offset:5120
	ds_read_b128 v[60:63], v154 offset:5136
	ds_read_b128 v[72:75], v154 offset:5632
	ds_read_b128 v[76:79], v154 offset:5648
	s_waitcnt lgkmcnt(6)
	v_pk_mul_f32 v[156:157], v[24:25], v[126:127]
	v_pk_mul_f32 v[90:91], v[28:29], v[122:123]
	v_pk_mul_f32 v[158:159], v[40:41], v[126:127]
	v_pk_fma_f32 v[156:157], v[124:125], v[26:27], v[156:157]
	v_pk_fma_f32 v[90:91], v[120:121], v[30:31], v[90:91]
	v_pk_fma_f32 v[158:159], v[124:125], v[42:43], v[158:159]
	v_pk_fma_f32 v[126:127], v[98:99], v[16:17], v[126:127] op_sel_hi:[0,1,1]
	v_pk_fma_f32 v[158:159], v[122:123], v[44:45], v[158:159]
	v_pk_fma_f32 v[124:125], v[98:99], v[18:19], v[124:125] op_sel_hi:[0,1,1]
	v_pk_add_f32 v[156:157], v[156:157], v[90:91]
	v_pk_fma_f32 v[158:159], v[120:121], v[46:47], v[158:159]
	v_add_f32_e32 v155, v156, v157
	v_pk_fma_f32 v[122:123], v[98:99], v[20:21], v[122:123] op_sel_hi:[0,1,1]
	v_pk_fma_f32 v[120:121], v[98:99], v[22:23], v[120:121] op_sel_hi:[0,1,1]
	ds_read_b128 v[40:43], v154 offset:4608
	ds_read_b128 v[44:47], v154 offset:4624
	v_add_f32_e32 v158, v158, v159
	v_add_f32_dpp v155, v155, v155 quad_perm:[1,0,3,2] row_mask:0xf bank_mask:0xf bound_ctrl:1
	s_mov_b32 s6, 0x2020202
	s_mov_b32 s7, 0x2020202
	v_add_f32_dpp v158, v158, v158 quad_perm:[1,0,3,2] row_mask:0xf bank_mask:0xf bound_ctrl:1
	v_add_f32_dpp v155, v155, v155 quad_perm:[2,3,0,1] row_mask:0xf bank_mask:0xf bound_ctrl:1
	s_nop 0
	v_add_f32_dpp v158, v158, v158 quad_perm:[2,3,0,1] row_mask:0xf bank_mask:0xf bound_ctrl:1
	v_add_f32_dpp v156, v155, v155 row_half_mirror row_mask:0xf bank_mask:0xf bound_ctrl:1
	v_pk_fma_f32 v[126:127], v[156:157], v[32:33], v[126:127] op_sel_hi:[0,1,1]
	v_pk_fma_f32 v[124:125], v[156:157], v[34:35], v[124:125] op_sel_hi:[0,1,1]
	v_add_f32_dpp v158, v158, v158 row_half_mirror row_mask:0xf bank_mask:0xf bound_ctrl:1
	v_pk_fma_f32 v[122:123], v[156:157], v[36:37], v[122:123] op_sel_hi:[0,1,1]
	v_pk_fma_f32 v[120:121], v[156:157], v[38:39], v[120:121] op_sel_hi:[0,1,1]
	v_cndmask_b32_e64 v94, v94, v158, s[6:7]
	ds_read_b128 v[24:27], v154 offset:6912
	ds_read_b128 v[28:31], v154 offset:6928
	ds_read_b128 v[16:19], v154 offset:6656
	ds_read_b128 v[20:23], v154 offset:6672
	ds_read_b128 v[32:35], v154 offset:7168
	ds_read_b128 v[36:39], v154 offset:7184
	ds_read2st64_b32 v[92:93], v153 offset0:29 offset1:35
	s_waitcnt lgkmcnt(7)
; #define LAS __attribute__((address_space(3)))
; DI unsigned pack2(float lo, float hi) { f32x2 v = {lo, hi}; return __builtin_bit_cast(unsigned, __builtin_convertvector(v, bf16x2_t)); }
; DI void scan_item(PP p, int l, int item, LAS unsigned char* lds) {
;     ...
;     for (int c = 0; c < NCH; ++c) {
;         if (wid >= 4) { if (c + 1 < NCH) { fill(c + 1); if (c + 2 < NCH) gl(c + 2); } }
;         else {
;             const LAS float* sp = buf + ((c & 1) * T) * 384;
;             f32x4 Ar0, Ar1, Aw0, Aw1, Ak0, Ak1, Aa0, Aa1, Ab0, Ab1; float Avv;
;             f32x4 Br0, Br1, Bw0, Bw1, Bk0, Bk1, Ba0, Ba1, Bb0, Bb1; float Bvv;
;             SC_LD(A, sp);
;             const ptrdiff_t ystep = dir ? -512 : 512;
;             u16* Yl = Yp + (size_t)steprow(b, dir, c * T) * 512 + (ptrdiff_t)ks * ystep;
; #pragma nounroll
;             for (int st = 0; st < T; st += 2) {
;                 SC_LD(B, sp + (st + 1) * 384);
;                 SC_STEP(A, st);
;                 if (st + 2 < T) SC_LD(A, sp + (st + 2) * 384);
;                 SC_STEP(B, st + 1);
;                 if ((st & 6) == 6) {
;                     const LAS float* rp = ypl + (ks * 68 - lane) + (lane & ~7);
;                     const f32x4 q0 = *(const LAS f32x4*)rp, q1 = *(const LAS f32x4*)(rp + 4);
;                     Yl[(ptrdiff_t)(st - 6) * ystep] = (u16)(pack2(((q0[0] + q0[1]) + (q0[2] + q0[3])) + ((q1[0] + q1[1]) + (q1[2] + q1[3])), 0.f) & 0xffffu);
;                 }
;             }
	v_pk_mul_f32 v[156:157], v[64:65], v[126:127]
	v_pk_mul_f32 v[90:91], v[68:69], v[122:123]
	v_pk_mul_f32 v[158:159], v[0:1], v[126:127]
	v_pk_fma_f32 v[156:157], v[124:125], v[66:67], v[156:157]
	v_pk_fma_f32 v[90:91], v[120:121], v[70:71], v[90:91]
	v_pk_fma_f32 v[158:159], v[124:125], v[2:3], v[158:159]
	v_pk_fma_f32 v[126:127], v[98:99], v[56:57], v[126:127] op_sel:[1,0,0] op_sel_hi:[1,1,1]
	v_pk_fma_f32 v[158:159], v[122:123], v[4:5], v[158:159]
	v_pk_fma_f32 v[124:125], v[98:99], v[58:59], v[124:125] op_sel:[1,0,0] op_sel_hi:[1,1,1]
	v_pk_add_f32 v[156:157], v[156:157], v[90:91]
	v_pk_fma_f32 v[158:159], v[120:121], v[6:7], v[158:159]
	v_add_f32_e32 v155, v156, v157
	v_pk_fma_f32 v[122:123], v[98:99], v[60:61], v[122:123] op_sel:[1,0,0] op_sel_hi:[1,1,1]
	v_pk_fma_f32 v[120:121], v[98:99], v[62:63], v[120:121] op_sel:[1,0,0] op_sel_hi:[1,1,1]
	ds_read_b128 v[0:3], v154 offset:6144
	ds_read_b128 v[4:7], v154 offset:6160
	v_add_f32_e32 v158, v158, v159
	v_add_f32_dpp v155, v155, v155 quad_perm:[1,0,3,2] row_mask:0xf bank_mask:0xf bound_ctrl:1
	s_mov_b32 s6, 0x4040404
	s_mov_b32 s7, 0x4040404
	v_add_f32_dpp v158, v158, v158 quad_perm:[1,0,3,2] row_mask:0xf bank_mask:0xf bound_ctrl:1
	v_add_f32_dpp v155, v155, v155 quad_perm:[2,3,0,1] row_mask:0xf bank_mask:0xf bound_ctrl:1
	s_nop 0
	v_add_f32_dpp v158, v158, v158 quad_perm:[2,3,0,1] row_mask:0xf bank_mask:0xf bound_ctrl:1
	v_add_f32_dpp v156, v155, v155 row_half_mirror row_mask:0xf bank_mask:0xf bound_ctrl:1
	v_pk_fma_f32 v[126:127], v[156:157], v[72:73], v[126:127] op_sel_hi:[0,1,1]
	v_pk_fma_f32 v[124:125], v[156:157], v[74:75], v[124:125] op_sel_hi:[0,1,1]
	v_add_f32_dpp v158, v158, v158 row_half_mirror row_mask:0xf bank_mask:0xf bound_ctrl:1
	v_pk_fma_f32 v[122:123], v[156:157], v[76:77], v[122:123] op_sel_hi:[0,1,1]
	v_pk_fma_f32 v[120:121], v[156:157], v[78:79], v[120:121] op_sel_hi:[0,1,1]
	v_cndmask_b32_e64 v94, v94, v158, s[6:7]
	ds_read_b128 v[64:67], v154 offset:8448
	ds_read_b128 v[68:71], v154 offset:8464
	ds_read_b128 v[56:59], v154 offset:8192
	ds_read_b128 v[60:63], v154 offset:8208
	ds_read_b128 v[72:75], v154 offset:8704
	ds_read_b128 v[76:79], v154 offset:8720
	s_waitcnt lgkmcnt(6)
	v_pk_mul_f32 v[156:157], v[24:25], v[126:127]
	v_pk_mul_f32 v[90:91], v[28:29], v[122:123]
	v_pk_mul_f32 v[158:159], v[40:41], v[126:127]
	v_pk_fma_f32 v[156:157], v[124:125], v[26:27], v[156:157]
	v_pk_fma_f32 v[90:91], v[120:121], v[30:31], v[90:91]
	v_pk_fma_f32 v[158:159], v[124:125], v[42:43], v[158:159]
	v_pk_fma_f32 v[126:127], v[92:93], v[16:17], v[126:127] op_sel_hi:[0,1,1]
	v_pk_fma_f32 v[158:159], v[122:123], v[44:45], v[158:159]
	v_pk_fma_f32 v[124:125], v[92:93], v[18:19], v[124:125] op_sel_hi:[0,1,1]
	v_pk_add_f32 v[156:157], v[156:157], v[90:91]
	v_pk_fma_f32 v[158:159], v[120:121], v[46:47], v[158:159]
	v_add_f32_e32 v155, v156, v157
	v_pk_fma_f32 v[122:123], v[92:93], v[20:21], v[122:123] op_sel_hi:[0,1,1]
	v_pk_fma_f32 v[120:121], v[92:93], v[22:23], v[120:121] op_sel_hi:[0,1,1]
	ds_read_b128 v[40:43], v154 offset:7680
	ds_read_b128 v[44:47], v154 offset:7696
	v_add_f32_e32 v158, v158, v159
	v_add_f32_dpp v155, v155, v155 quad_perm:[1,0,3,2] row_mask:0xf bank_mask:0xf bound_ctrl:1
	s_mov_b32 s6, 0x8080808
	s_mov_b32 s7, 0x8080808
	v_add_f32_dpp v158, v158, v158 quad_perm:[1,0,3,2] row_mask:0xf bank_mask:0xf bound_ctrl:1
	v_add_f32_dpp v155, v155, v155 quad_perm:[2,3,0,1] row_mask:0xf bank_mask:0xf bound_ctrl:1
	s_nop 0
	v_add_f32_dpp v158, v158, v158 quad_perm:[2,3,0,1] row_mask:0xf bank_mask:0xf bound_ctrl:1
	v_add_f32_dpp v156, v155, v155 row_half_mirror row_mask:0xf bank_mask:0xf bound_ctrl:1
	v_pk_fma_f32 v[126:127], v[156:157], v[32:33], v[126:127] op_sel_hi:[0,1,1]
	v_pk_fma_f32 v[124:125], v[156:157], v[34:35], v[124:125] op_sel_hi:[0,1,1]
	v_add_f32_dpp v158, v158, v158 row_half_mirror row_mask:0xf bank_mask:0xf bound_ctrl:1
	v_pk_fma_f32 v[122:123], v[156:157], v[36:37], v[122:123] op_sel_hi:[0,1,1]
	v_pk_fma_f32 v[120:121], v[156:157], v[38:39], v[120:121] op_sel_hi:[0,1,1]
	v_cndmask_b32_e64 v94, v94, v158, s[6:7]
	ds_read_b128 v[24:27], v154 offset:9984
	ds_read_b128 v[28:31], v154 offset:10000
	ds_read_b128 v[16:19], v154 offset:9728
	ds_read_b128 v[20:23], v154 offset:9744
	ds_read_b128 v[32:35], v154 offset:10240
	ds_read_b128 v[36:39], v154 offset:10256
	ds_read2st64_b32 v[98:99], v153 offset0:41 offset1:47
	s_waitcnt lgkmcnt(7)
	v_pk_mul_f32 v[156:157], v[64:65], v[126:127]
	v_pk_mul_f32 v[90:91], v[68:69], v[122:123]
	v_pk_mul_f32 v[158:159], v[0:1], v[126:127]
	v_pk_fma_f32 v[156:157], v[124:125], v[66:67], v[156:157]
	v_pk_fma_f32 v[90:91], v[120:121], v[70:71], v[90:91]
	v_pk_fma_f32 v[158:159], v[124:125], v[2:3], v[158:159]
	v_pk_fma_f32 v[126:127], v[92:93], v[56:57], v[126:127] op_sel:[1,0,0] op_sel_hi:[1,1,1]
	v_pk_fma_f32 v[158:159], v[122:123], v[4:5], v[158:159]
	v_pk_fma_f32 v[124:125], v[92:93], v[58:59], v[124:125] op_sel:[1,0,0] op_sel_hi:[1,1,1]
	v_pk_add_f32 v[156:157], v[156:157], v[90:91]
	v_pk_fma_f32 v[158:159], v[120:121], v[6:7], v[158:159]
	v_add_f32_e32 v155, v156, v157
	v_pk_fma_f32 v[122:123], v[92:93], v[60:61], v[122:123] op_sel:[1,0,0] op_sel_hi:[1,1,1]
	v_pk_fma_f32 v[120:121], v[92:93], v[62:63], v[120:121] op_sel:[1,0,0] op_sel_hi:[1,1,1]
	ds_read_b128 v[0:3], v154 offset:9216
	ds_read_b128 v[4:7], v154 offset:9232
	v_add_f32_e32 v158, v158, v159
	v_add_f32_dpp v155, v155, v155 quad_perm:[1,0,3,2] row_mask:0xf bank_mask:0xf bound_ctrl:1
	s_mov_b32 s6, 0x10101010
	s_mov_b32 s7, 0x10101010
	v_add_f32_dpp v158, v158, v158 quad_perm:[1,0,3,2] row_mask:0xf bank_mask:0xf bound_ctrl:1
	v_add_f32_dpp v155, v155, v155 quad_perm:[2,3,0,1] row_mask:0xf bank_mask:0xf bound_ctrl:1
	s_nop 0
	v_add_f32_dpp v158, v158, v158 quad_perm:[2,3,0,1] row_mask:0xf bank_mask:0xf bound_ctrl:1
	v_add_f32_dpp v156, v155, v155 row_half_mirror row_mask:0xf bank_mask:0xf bound_ctrl:1
	v_pk_fma_f32 v[126:127], v[156:157], v[72:73], v[126:127] op_sel_hi:[0,1,1]
	v_pk_fma_f32 v[124:125], v[156:157], v[74:75], v[124:125] op_sel_hi:[0,1,1]
	v_add_f32_dpp v158, v158, v158 row_half_mirror row_mask:0xf bank_mask:0xf bound_ctrl:1
	v_pk_fma_f32 v[122:123], v[156:157], v[76:77], v[122:123] op_sel_hi:[0,1,1]
	v_pk_fma_f32 v[120:121], v[156:157], v[78:79], v[120:121] op_sel_hi:[0,1,1]
	v_cndmask_b32_e64 v94, v94, v158, s[6:7]
	ds_read_b128 v[64:67], v154 offset:11520
	ds_read_b128 v[68:71], v154 offset:11536
	ds_read_b128 v[56:59], v154 offset:11264
	ds_read_b128 v[60:63], v154 offset:11280
	ds_read_b128 v[72:75], v154 offset:11776
	ds_read_b128 v[76:79], v154 offset:11792
	ds_read_b128 v[48:51], v154 offset:11008
	ds_read_b128 v[52:55], v154 offset:11024
	s_waitcnt lgkmcnt(8)
; #define LAS __attribute__((address_space(3)))
; DI unsigned pack2(float lo, float hi) { f32x2 v = {lo, hi}; return __builtin_bit_cast(unsigned, __builtin_convertvector(v, bf16x2_t)); }
; DI void scan_item(PP p, int l, int item, LAS unsigned char* lds) {
;     ...
;     for (int c = 0; c < NCH; ++c) {
;         if (wid >= 4) { if (c + 1 < NCH) { fill(c + 1); if (c + 2 < NCH) gl(c + 2); } }
;         else {
;             const LAS float* sp = buf + ((c & 1) * T) * 384;
;             f32x4 Ar0, Ar1, Aw0, Aw1, Ak0, Ak1, Aa0, Aa1, Ab0, Ab1; float Avv;
;             f32x4 Br0, Br1, Bw0, Bw1, Bk0, Bk1, Ba0, Ba1, Bb0, Bb1; float Bvv;
;             SC_LD(A, sp);
;             const ptrdiff_t ystep = dir ? -512 : 512;
;             u16* Yl = Yp + (size_t)steprow(b, dir, c * T) * 512 + (ptrdiff_t)ks * ystep;
; #pragma nounroll
;             for (int st = 0; st < T; st += 2) {
;                 SC_LD(B, sp + (st + 1) * 384);
;                 SC_STEP(A, st);
;                 if (st + 2 < T) SC_LD(A, sp + (st + 2) * 384);
;                 SC_STEP(B, st + 1);
;                 if ((st & 6) == 6) {
;                     const LAS float* rp = ypl + (ks * 68 - lane) + (lane & ~7);
;                     const f32x4 q0 = *(const LAS f32x4*)rp, q1 = *(const LAS f32x4*)(rp + 4);
;                     Yl[(ptrdiff_t)(st - 6) * ystep] = (u16)(pack2(((q0[0] + q0[1]) + (q0[2] + q0[3])) + ((q1[0] + q1[1]) + (q1[2] + q1[3])), 0.f) & 0xffffu);
;                 }
;             }
	v_pk_mul_f32 v[156:157], v[24:25], v[126:127]
	v_pk_mul_f32 v[90:91], v[28:29], v[122:123]
	v_pk_mul_f32 v[158:159], v[40:41], v[126:127]
	v_pk_fma_f32 v[156:157], v[124:125], v[26:27], v[156:157]
	v_pk_fma_f32 v[90:91], v[120:121], v[30:31], v[90:91]
	v_pk_fma_f32 v[158:159], v[124:125], v[42:43], v[158:159]
	v_pk_fma_f32 v[126:127], v[98:99], v[16:17], v[126:127] op_sel_hi:[0,1,1]
	v_pk_fma_f32 v[158:159], v[122:123], v[44:45], v[158:159]
	v_pk_fma_f32 v[124:125], v[98:99], v[18:19], v[124:125] op_sel_hi:[0,1,1]
	v_pk_add_f32 v[156:157], v[156:157], v[90:91]
	v_pk_fma_f32 v[158:159], v[120:121], v[46:47], v[158:159]
	v_add_f32_e32 v155, v156, v157
	v_pk_fma_f32 v[122:123], v[98:99], v[20:21], v[122:123] op_sel_hi:[0,1,1]
	v_pk_fma_f32 v[120:121], v[98:99], v[22:23], v[120:121] op_sel_hi:[0,1,1]
	ds_read_b128 v[40:43], v154 offset:10752
	ds_read_b128 v[44:47], v154 offset:10768
	v_add_f32_e32 v158, v158, v159
	v_add_f32_dpp v155, v155, v155 quad_perm:[1,0,3,2] row_mask:0xf bank_mask:0xf bound_ctrl:1
	s_mov_b32 s6, 0x20202020
	s_mov_b32 s7, 0x20202020
	v_add_f32_dpp v158, v158, v158 quad_perm:[1,0,3,2] row_mask:0xf bank_mask:0xf bound_ctrl:1
	v_add_f32_dpp v155, v155, v155 quad_perm:[2,3,0,1] row_mask:0xf bank_mask:0xf bound_ctrl:1
	s_nop 0
	v_add_f32_dpp v158, v158, v158 quad_perm:[2,3,0,1] row_mask:0xf bank_mask:0xf bound_ctrl:1
	v_add_f32_dpp v156, v155, v155 row_half_mirror row_mask:0xf bank_mask:0xf bound_ctrl:1
	v_pk_fma_f32 v[126:127], v[156:157], v[32:33], v[126:127] op_sel_hi:[0,1,1]
	v_pk_fma_f32 v[124:125], v[156:157], v[34:35], v[124:125] op_sel_hi:[0,1,1]
	v_add_f32_dpp v158, v158, v158 row_half_mirror row_mask:0xf bank_mask:0xf bound_ctrl:1
	v_pk_fma_f32 v[122:123], v[156:157], v[36:37], v[122:123] op_sel_hi:[0,1,1]
	v_pk_fma_f32 v[120:121], v[156:157], v[38:39], v[120:121] op_sel_hi:[0,1,1]
	v_cndmask_b32_e64 v94, v94, v158, s[6:7]
	ds_read_b128 v[24:27], v154 offset:13056
	ds_read_b128 v[28:31], v154 offset:13072
	ds_read_b128 v[16:19], v154 offset:12800
	ds_read_b128 v[20:23], v154 offset:12816
	ds_read_b128 v[32:35], v154 offset:13312
	ds_read_b128 v[36:39], v154 offset:13328
	ds_read2st64_b32 v[92:93], v153 offset0:53 offset1:59
	s_waitcnt lgkmcnt(7)
	v_pk_mul_f32 v[156:157], v[64:65], v[126:127]
	v_pk_mul_f32 v[90:91], v[68:69], v[122:123]
	v_pk_mul_f32 v[158:159], v[0:1], v[126:127]
	v_pk_fma_f32 v[156:157], v[124:125], v[66:67], v[156:157]
	v_pk_fma_f32 v[90:91], v[120:121], v[70:71], v[90:91]
	v_pk_fma_f32 v[158:159], v[124:125], v[2:3], v[158:159]
	v_pk_fma_f32 v[126:127], v[98:99], v[56:57], v[126:127] op_sel:[1,0,0] op_sel_hi:[1,1,1]
	v_pk_fma_f32 v[158:159], v[122:123], v[4:5], v[158:159]
	v_pk_fma_f32 v[124:125], v[98:99], v[58:59], v[124:125] op_sel:[1,0,0] op_sel_hi:[1,1,1]
	v_pk_add_f32 v[156:157], v[156:157], v[90:91]
	v_pk_fma_f32 v[158:159], v[120:121], v[6:7], v[158:159]
	v_add_f32_e32 v155, v156, v157
	v_pk_fma_f32 v[122:123], v[98:99], v[60:61], v[122:123] op_sel:[1,0,0] op_sel_hi:[1,1,1]
	v_pk_fma_f32 v[120:121], v[98:99], v[62:63], v[120:121] op_sel:[1,0,0] op_sel_hi:[1,1,1]
	ds_read_b128 v[0:3], v154 offset:12288
	ds_read_b128 v[4:7], v154 offset:12304
	v_add_f32_e32 v158, v158, v159
	v_add_f32_dpp v155, v155, v155 quad_perm:[1,0,3,2] row_mask:0xf bank_mask:0xf bound_ctrl:1
	s_mov_b32 s6, 0x40404040
	s_mov_b32 s7, 0x40404040
	v_add_f32_dpp v158, v158, v158 quad_perm:[1,0,3,2] row_mask:0xf bank_mask:0xf bound_ctrl:1
	v_add_f32_dpp v155, v155, v155 quad_perm:[2,3,0,1] row_mask:0xf bank_mask:0xf bound_ctrl:1
	s_nop 0
	v_add_f32_dpp v158, v158, v158 quad_perm:[2,3,0,1] row_mask:0xf bank_mask:0xf bound_ctrl:1
	v_add_f32_dpp v156, v155, v155 row_half_mirror row_mask:0xf bank_mask:0xf bound_ctrl:1
	v_pk_fma_f32 v[126:127], v[156:157], v[72:73], v[126:127] op_sel_hi:[0,1,1]
	v_pk_fma_f32 v[124:125], v[156:157], v[74:75], v[124:125] op_sel_hi:[0,1,1]
	v_add_f32_dpp v158, v158, v158 row_half_mirror row_mask:0xf bank_mask:0xf bound_ctrl:1
	v_pk_fma_f32 v[122:123], v[156:157], v[76:77], v[122:123] op_sel_hi:[0,1,1]
	v_pk_fma_f32 v[120:121], v[156:157], v[78:79], v[120:121] op_sel_hi:[0,1,1]
	v_cndmask_b32_e64 v94, v94, v158, s[6:7]
	v_pk_mul_f32 v[158:159], v[40:41], v[126:127]
	s_nop 0
	v_pk_fma_f32 v[158:159], v[124:125], v[42:43], v[158:159]
	s_nop 0
	v_pk_fma_f32 v[158:159], v[122:123], v[44:45], v[158:159]
	s_nop 0
	v_pk_fma_f32 v[158:159], v[120:121], v[46:47], v[158:159]
	s_nop 0
	v_add_f32_e32 v158, v158, v159
	s_mov_b32 s6, 0x80808080
	s_mov_b32 s7, 0x80808080
	v_add_f32_dpp v158, v158, v158 quad_perm:[1,0,3,2] row_mask:0xf bank_mask:0xf bound_ctrl:1
	s_nop 1
	v_add_f32_dpp v158, v158, v158 quad_perm:[2,3,0,1] row_mask:0xf bank_mask:0xf bound_ctrl:1
	s_nop 1
	v_add_f32_dpp v158, v158, v158 row_half_mirror row_mask:0xf bank_mask:0xf bound_ctrl:1
	v_pk_mul_f32 v[126:127], v[48:49], v[126:127]
	v_pk_mul_f32 v[124:125], v[50:51], v[124:125]
	v_pk_mul_f32 v[122:123], v[52:53], v[122:123]
	v_pk_mul_f32 v[120:121], v[54:55], v[120:121]
	v_cndmask_b32_e64 v94, v94, v158, s[6:7]
	ds_read_b128 v[40:43], v154 offset:13824
	ds_read_b128 v[44:47], v154 offset:13840
	ds_read_b128 v[64:67], v154 offset:14592
	ds_read_b128 v[68:71], v154 offset:14608
	ds_read_b128 v[56:59], v154 offset:14336
	ds_read_b128 v[60:63], v154 offset:14352
	ds_read_b128 v[72:75], v154 offset:14848
	ds_read_b128 v[76:79], v154 offset:14864
	s_waitcnt lgkmcnt(8)
; #define LAS __attribute__((address_space(3)))
; DI unsigned pack2(float lo, float hi) { f32x2 v = {lo, hi}; return __builtin_bit_cast(unsigned, __builtin_convertvector(v, bf16x2_t)); }
; DI void scan_item(PP p, int l, int item, LAS unsigned char* lds) {
;     ...
;     for (int c = 0; c < NCH; ++c) {
;         if (wid >= 4) { if (c + 1 < NCH) { fill(c + 1); if (c + 2 < NCH) gl(c + 2); } }
;         else {
;             const LAS float* sp = buf + ((c & 1) * T) * 384;
;             f32x4 Ar0, Ar1, Aw0, Aw1, Ak0, Ak1, Aa0, Aa1, Ab0, Ab1; float Avv;
;             f32x4 Br0, Br1, Bw0, Bw1, Bk0, Bk1, Ba0, Ba1, Bb0, Bb1; float Bvv;
;             SC_LD(A, sp);
;             const ptrdiff_t ystep = dir ? -512 : 512;
;             u16* Yl = Yp + (size_t)steprow(b, dir, c * T) * 512 + (ptrdiff_t)ks * ystep;
; #pragma nounroll
;             for (int st = 0; st < T; st += 2) {
;                 SC_LD(B, sp + (st + 1) * 384);
;                 SC_STEP(A, st);
;                 if (st + 2 < T) SC_LD(A, sp + (st + 2) * 384);
;                 SC_STEP(B, st + 1);
;                 if ((st & 6) == 6) {
;                     const LAS float* rp = ypl + (ks * 68 - lane) + (lane & ~7);
;                     const f32x4 q0 = *(const LAS f32x4*)rp, q1 = *(const LAS f32x4*)(rp + 4);
;                     Yl[(ptrdiff_t)(st - 6) * ystep] = (u16)(pack2(((q0[0] + q0[1]) + (q0[2] + q0[3])) + ((q1[0] + q1[1]) + (q1[2] + q1[3])), 0.f) & 0xffffu);
;                 }
;             }
	v_pk_mul_f32 v[156:157], v[24:25], v[126:127]
	v_pk_mul_f32 v[90:91], v[28:29], v[122:123]
	v_pk_fma_f32 v[126:127], v[92:93], v[16:17], v[126:127] op_sel_hi:[0,1,1]
	v_pk_fma_f32 v[156:157], v[124:125], v[26:27], v[156:157]
	v_pk_fma_f32 v[90:91], v[120:121], v[30:31], v[90:91]
	v_pk_fma_f32 v[124:125], v[92:93], v[18:19], v[124:125] op_sel_hi:[0,1,1]
	v_pk_fma_f32 v[122:123], v[92:93], v[20:21], v[122:123] op_sel_hi:[0,1,1]
	v_pk_add_f32 v[156:157], v[156:157], v[90:91]
	v_pk_fma_f32 v[120:121], v[92:93], v[22:23], v[120:121] op_sel_hi:[0,1,1]
	v_add_f32_e32 v155, v156, v157
	s_nop 1
	v_add_f32_dpp v155, v155, v155 quad_perm:[1,0,3,2] row_mask:0xf bank_mask:0xf bound_ctrl:1
	s_nop 1
	v_add_f32_dpp v155, v155, v155 quad_perm:[2,3,0,1] row_mask:0xf bank_mask:0xf bound_ctrl:1
	s_nop 1
	v_add_f32_dpp v156, v155, v155 row_half_mirror row_mask:0xf bank_mask:0xf bound_ctrl:1
	v_pk_fma_f32 v[126:127], v[156:157], v[32:33], v[126:127] op_sel_hi:[0,1,1]
	v_pk_fma_f32 v[124:125], v[156:157], v[34:35], v[124:125] op_sel_hi:[0,1,1]
	v_pk_fma_f32 v[122:123], v[156:157], v[36:37], v[122:123] op_sel_hi:[0,1,1]
	v_pk_fma_f32 v[120:121], v[156:157], v[38:39], v[120:121] op_sel_hi:[0,1,1]
	v_cvt_pk_bf16_f32 v82, v94, v94
	global_store_short v[118:119], v82, off
	v_lshl_add_u64 v[118:119], s[8:9], 0, v[118:119]
	ds_read_b128 v[24:27], v154 offset:16128
	ds_read_b128 v[28:31], v154 offset:16144
	ds_read_b128 v[16:19], v154 offset:15872
	ds_read_b128 v[20:23], v154 offset:15888
	ds_read_b128 v[32:35], v154 offset:16384
	ds_read_b128 v[36:39], v154 offset:16400
	ds_read2st64_b32 v[98:99], v153 offset0:65 offset1:71
	s_waitcnt lgkmcnt(7)
	v_pk_mul_f32 v[156:157], v[64:65], v[126:127]
	v_pk_mul_f32 v[90:91], v[68:69], v[122:123]
	v_pk_mul_f32 v[158:159], v[0:1], v[126:127]
	v_pk_fma_f32 v[156:157], v[124:125], v[66:67], v[156:157]
	v_pk_fma_f32 v[90:91], v[120:121], v[70:71], v[90:91]
	v_pk_fma_f32 v[158:159], v[124:125], v[2:3], v[158:159]
	v_pk_fma_f32 v[126:127], v[92:93], v[56:57], v[126:127] op_sel:[1,0,0] op_sel_hi:[1,1,1]
	v_pk_fma_f32 v[158:159], v[122:123], v[4:5], v[158:159]
	v_pk_fma_f32 v[124:125], v[92:93], v[58:59], v[124:125] op_sel:[1,0,0] op_sel_hi:[1,1,1]
	v_pk_add_f32 v[156:157], v[156:157], v[90:91]
	v_pk_fma_f32 v[158:159], v[120:121], v[6:7], v[158:159]
	v_add_f32_e32 v155, v156, v157
	v_pk_fma_f32 v[122:123], v[92:93], v[60:61], v[122:123] op_sel:[1,0,0] op_sel_hi:[1,1,1]
	v_pk_fma_f32 v[120:121], v[92:93], v[62:63], v[120:121] op_sel:[1,0,0] op_sel_hi:[1,1,1]
	ds_read_b128 v[0:3], v154 offset:15360
	ds_read_b128 v[4:7], v154 offset:15376
	v_add_f32_e32 v158, v158, v159
	v_add_f32_dpp v155, v155, v155 quad_perm:[1,0,3,2] row_mask:0xf bank_mask:0xf bound_ctrl:1
	s_mov_b32 s6, 0x1010101
	s_mov_b32 s7, 0x1010101
	v_add_f32_dpp v158, v158, v158 quad_perm:[1,0,3,2] row_mask:0xf bank_mask:0xf bound_ctrl:1
	v_add_f32_dpp v155, v155, v155 quad_perm:[2,3,0,1] row_mask:0xf bank_mask:0xf bound_ctrl:1
	s_nop 0
	v_add_f32_dpp v158, v158, v158 quad_perm:[2,3,0,1] row_mask:0xf bank_mask:0xf bound_ctrl:1
	v_add_f32_dpp v156, v155, v155 row_half_mirror row_mask:0xf bank_mask:0xf bound_ctrl:1
	v_pk_fma_f32 v[126:127], v[156:157], v[72:73], v[126:127] op_sel_hi:[0,1,1]
	v_pk_fma_f32 v[124:125], v[156:157], v[74:75], v[124:125] op_sel_hi:[0,1,1]
	v_add_f32_dpp v158, v158, v158 row_half_mirror row_mask:0xf bank_mask:0xf bound_ctrl:1
	v_pk_fma_f32 v[122:123], v[156:157], v[76:77], v[122:123] op_sel_hi:[0,1,1]
	v_pk_fma_f32 v[120:121], v[156:157], v[78:79], v[120:121] op_sel_hi:[0,1,1]
	v_cndmask_b32_e64 v94, v94, v158, s[6:7]
	ds_read_b128 v[64:67], v154 offset:17664
	ds_read_b128 v[68:71], v154 offset:17680
	ds_read_b128 v[56:59], v154 offset:17408
	ds_read_b128 v[60:63], v154 offset:17424
	ds_read_b128 v[72:75], v154 offset:17920
	ds_read_b128 v[76:79], v154 offset:17936
	s_waitcnt lgkmcnt(6)
	v_pk_mul_f32 v[156:157], v[24:25], v[126:127]
	v_pk_mul_f32 v[90:91], v[28:29], v[122:123]
	v_pk_mul_f32 v[158:159], v[40:41], v[126:127]
	v_pk_fma_f32 v[156:157], v[124:125], v[26:27], v[156:157]
	v_pk_fma_f32 v[90:91], v[120:121], v[30:31], v[90:91]
	v_pk_fma_f32 v[158:159], v[124:125], v[42:43], v[158:159]
	v_pk_fma_f32 v[126:127], v[98:99], v[16:17], v[126:127] op_sel_hi:[0,1,1]
	v_pk_fma_f32 v[158:159], v[122:123], v[44:45], v[158:159]
	v_pk_fma_f32 v[124:125], v[98:99], v[18:19], v[124:125] op_sel_hi:[0,1,1]
	v_pk_add_f32 v[156:157], v[156:157], v[90:91]
	v_pk_fma_f32 v[158:159], v[120:121], v[46:47], v[158:159]
	v_add_f32_e32 v155, v156, v157
	v_pk_fma_f32 v[122:123], v[98:99], v[20:21], v[122:123] op_sel_hi:[0,1,1]
	v_pk_fma_f32 v[120:121], v[98:99], v[22:23], v[120:121] op_sel_hi:[0,1,1]
	ds_read_b128 v[40:43], v154 offset:16896
	ds_read_b128 v[44:47], v154 offset:16912
	v_add_f32_e32 v158, v158, v159
	v_add_f32_dpp v155, v155, v155 quad_perm:[1,0,3,2] row_mask:0xf bank_mask:0xf bound_ctrl:1
	s_mov_b32 s6, 0x2020202
	s_mov_b32 s7, 0x2020202
	v_add_f32_dpp v158, v158, v158 quad_perm:[1,0,3,2] row_mask:0xf bank_mask:0xf bound_ctrl:1
	v_add_f32_dpp v155, v155, v155 quad_perm:[2,3,0,1] row_mask:0xf bank_mask:0xf bound_ctrl:1
	s_nop 0
	v_add_f32_dpp v158, v158, v158 quad_perm:[2,3,0,1] row_mask:0xf bank_mask:0xf bound_ctrl:1
	v_add_f32_dpp v156, v155, v155 row_half_mirror row_mask:0xf bank_mask:0xf bound_ctrl:1
	v_pk_fma_f32 v[126:127], v[156:157], v[32:33], v[126:127] op_sel_hi:[0,1,1]
	v_pk_fma_f32 v[124:125], v[156:157], v[34:35], v[124:125] op_sel_hi:[0,1,1]
	v_add_f32_dpp v158, v158, v158 row_half_mirror row_mask:0xf bank_mask:0xf bound_ctrl:1
	v_pk_fma_f32 v[122:123], v[156:157], v[36:37], v[122:123] op_sel_hi:[0,1,1]
	v_pk_fma_f32 v[120:121], v[156:157], v[38:39], v[120:121] op_sel_hi:[0,1,1]
	v_cndmask_b32_e64 v94, v94, v158, s[6:7]
	ds_read_b128 v[24:27], v154 offset:19200
	ds_read_b128 v[28:31], v154 offset:19216
	ds_read_b128 v[16:19], v154 offset:18944
	ds_read_b128 v[20:23], v154 offset:18960
	ds_read_b128 v[32:35], v154 offset:19456
	ds_read_b128 v[36:39], v154 offset:19472
	ds_read2st64_b32 v[92:93], v153 offset0:77 offset1:83
	s_waitcnt lgkmcnt(7)
; #define LAS __attribute__((address_space(3)))
; DI unsigned pack2(float lo, float hi) { f32x2 v = {lo, hi}; return __builtin_bit_cast(unsigned, __builtin_convertvector(v, bf16x2_t)); }
; DI void scan_item(PP p, int l, int item, LAS unsigned char* lds) {
;     ...
;     for (int c = 0; c < NCH; ++c) {
;         if (wid >= 4) { if (c + 1 < NCH) { fill(c + 1); if (c + 2 < NCH) gl(c + 2); } }
;         else {
;             const LAS float* sp = buf + ((c & 1) * T) * 384;
;             f32x4 Ar0, Ar1, Aw0, Aw1, Ak0, Ak1, Aa0, Aa1, Ab0, Ab1; float Avv;
;             f32x4 Br0, Br1, Bw0, Bw1, Bk0, Bk1, Ba0, Ba1, Bb0, Bb1; float Bvv;
;             SC_LD(A, sp);
;             const ptrdiff_t ystep = dir ? -512 : 512;
;             u16* Yl = Yp + (size_t)steprow(b, dir, c * T) * 512 + (ptrdiff_t)ks * ystep;
; #pragma nounroll
;             for (int st = 0; st < T; st += 2) {
;                 SC_LD(B, sp + (st + 1) * 384);
;                 SC_STEP(A, st);
;                 if (st + 2 < T) SC_LD(A, sp + (st + 2) * 384);
;                 SC_STEP(B, st + 1);
;                 if ((st & 6) == 6) {
;                     const LAS float* rp = ypl + (ks * 68 - lane) + (lane & ~7);
;                     const f32x4 q0 = *(const LAS f32x4*)rp, q1 = *(const LAS f32x4*)(rp + 4);
;                     Yl[(ptrdiff_t)(st - 6) * ystep] = (u16)(pack2(((q0[0] + q0[1]) + (q0[2] + q0[3])) + ((q1[0] + q1[1]) + (q1[2] + q1[3])), 0.f) & 0xffffu);
;                 }
	v_pk_mul_f32 v[156:157], v[64:65], v[126:127]
	v_pk_mul_f32 v[90:91], v[68:69], v[122:123]
	v_pk_mul_f32 v[158:159], v[0:1], v[126:127]
	v_pk_fma_f32 v[156:157], v[124:125], v[66:67], v[156:157]
	v_pk_fma_f32 v[90:91], v[120:121], v[70:71], v[90:91]
	v_pk_fma_f32 v[158:159], v[124:125], v[2:3], v[158:159]
	v_pk_fma_f32 v[126:127], v[98:99], v[56:57], v[126:127] op_sel:[1,0,0] op_sel_hi:[1,1,1]
	v_pk_fma_f32 v[158:159], v[122:123], v[4:5], v[158:159]
	v_pk_fma_f32 v[124:125], v[98:99], v[58:59], v[124:125] op_sel:[1,0,0] op_sel_hi:[1,1,1]
	v_pk_add_f32 v[156:157], v[156:157], v[90:91]
	v_pk_fma_f32 v[158:159], v[120:121], v[6:7], v[158:159]
	v_add_f32_e32 v155, v156, v157
	v_pk_fma_f32 v[122:123], v[98:99], v[60:61], v[122:123] op_sel:[1,0,0] op_sel_hi:[1,1,1]
	v_pk_fma_f32 v[120:121], v[98:99], v[62:63], v[120:121] op_sel:[1,0,0] op_sel_hi:[1,1,1]
	ds_read_b128 v[0:3], v154 offset:18432
	ds_read_b128 v[4:7], v154 offset:18448
	v_add_f32_e32 v158, v158, v159
	v_add_f32_dpp v155, v155, v155 quad_perm:[1,0,3,2] row_mask:0xf bank_mask:0xf bound_ctrl:1
	s_mov_b32 s6, 0x4040404
	s_mov_b32 s7, 0x4040404
	v_add_f32_dpp v158, v158, v158 quad_perm:[1,0,3,2] row_mask:0xf bank_mask:0xf bound_ctrl:1
	v_add_f32_dpp v155, v155, v155 quad_perm:[2,3,0,1] row_mask:0xf bank_mask:0xf bound_ctrl:1
	s_nop 0
	v_add_f32_dpp v158, v158, v158 quad_perm:[2,3,0,1] row_mask:0xf bank_mask:0xf bound_ctrl:1
	v_add_f32_dpp v156, v155, v155 row_half_mirror row_mask:0xf bank_mask:0xf bound_ctrl:1
	v_pk_fma_f32 v[126:127], v[156:157], v[72:73], v[126:127] op_sel_hi:[0,1,1]
	v_pk_fma_f32 v[124:125], v[156:157], v[74:75], v[124:125] op_sel_hi:[0,1,1]
	v_add_f32_dpp v158, v158, v158 row_half_mirror row_mask:0xf bank_mask:0xf bound_ctrl:1
	v_pk_fma_f32 v[122:123], v[156:157], v[76:77], v[122:123] op_sel_hi:[0,1,1]
	v_pk_fma_f32 v[120:121], v[156:157], v[78:79], v[120:121] op_sel_hi:[0,1,1]
	v_cndmask_b32_e64 v94, v94, v158, s[6:7]
	ds_read_b128 v[64:67], v154 offset:20736
	ds_read_b128 v[68:71], v154 offset:20752
	ds_read_b128 v[56:59], v154 offset:20480
	ds_read_b128 v[60:63], v154 offset:20496
	ds_read_b128 v[72:75], v154 offset:20992
	ds_read_b128 v[76:79], v154 offset:21008
	s_waitcnt lgkmcnt(6)
	v_pk_mul_f32 v[156:157], v[24:25], v[126:127]
	v_pk_mul_f32 v[90:91], v[28:29], v[122:123]
	v_pk_mul_f32 v[158:159], v[40:41], v[126:127]
	v_pk_fma_f32 v[156:157], v[124:125], v[26:27], v[156:157]
	v_pk_fma_f32 v[90:91], v[120:121], v[30:31], v[90:91]
	v_pk_fma_f32 v[158:159], v[124:125], v[42:43], v[158:159]
	v_pk_fma_f32 v[126:127], v[92:93], v[16:17], v[126:127] op_sel_hi:[0,1,1]
	v_pk_fma_f32 v[158:159], v[122:123], v[44:45], v[158:159]
	v_pk_fma_f32 v[124:125], v[92:93], v[18:19], v[124:125] op_sel_hi:[0,1,1]
	v_pk_add_f32 v[156:157], v[156:157], v[90:91]
	v_pk_fma_f32 v[158:159], v[120:121], v[46:47], v[158:159]
	v_add_f32_e32 v155, v156, v157
	v_pk_fma_f32 v[122:123], v[92:93], v[20:21], v[122:123] op_sel_hi:[0,1,1]
	v_pk_fma_f32 v[120:121], v[92:93], v[22:23], v[120:121] op_sel_hi:[0,1,1]
	ds_read_b128 v[40:43], v154 offset:19968
	ds_read_b128 v[44:47], v154 offset:19984
	v_add_f32_e32 v158, v158, v159
	v_add_f32_dpp v155, v155, v155 quad_perm:[1,0,3,2] row_mask:0xf bank_mask:0xf bound_ctrl:1
	s_mov_b32 s6, 0x8080808
	s_mov_b32 s7, 0x8080808
	v_add_f32_dpp v158, v158, v158 quad_perm:[1,0,3,2] row_mask:0xf bank_mask:0xf bound_ctrl:1
	v_add_f32_dpp v155, v155, v155 quad_perm:[2,3,0,1] row_mask:0xf bank_mask:0xf bound_ctrl:1
	s_nop 0
	v_add_f32_dpp v158, v158, v158 quad_perm:[2,3,0,1] row_mask:0xf bank_mask:0xf bound_ctrl:1
	v_add_f32_dpp v156, v155, v155 row_half_mirror row_mask:0xf bank_mask:0xf bound_ctrl:1
	v_pk_fma_f32 v[126:127], v[156:157], v[32:33], v[126:127] op_sel_hi:[0,1,1]
	v_pk_fma_f32 v[124:125], v[156:157], v[34:35], v[124:125] op_sel_hi:[0,1,1]
	v_add_f32_dpp v158, v158, v158 row_half_mirror row_mask:0xf bank_mask:0xf bound_ctrl:1
	v_pk_fma_f32 v[122:123], v[156:157], v[36:37], v[122:123] op_sel_hi:[0,1,1]
	v_pk_fma_f32 v[120:121], v[156:157], v[38:39], v[120:121] op_sel_hi:[0,1,1]
	v_cndmask_b32_e64 v94, v94, v158, s[6:7]
	ds_read_b128 v[24:27], v154 offset:22272
	ds_read_b128 v[28:31], v154 offset:22288
	ds_read_b128 v[16:19], v154 offset:22016
	ds_read_b128 v[20:23], v154 offset:22032
	ds_read_b128 v[32:35], v154 offset:22528
	ds_read_b128 v[36:39], v154 offset:22544
	ds_read2st64_b32 v[98:99], v153 offset0:89 offset1:95
	s_waitcnt lgkmcnt(7)
	v_pk_mul_f32 v[156:157], v[64:65], v[126:127]
	v_pk_mul_f32 v[90:91], v[68:69], v[122:123]
	v_pk_mul_f32 v[158:159], v[0:1], v[126:127]
	v_pk_fma_f32 v[156:157], v[124:125], v[66:67], v[156:157]
	v_pk_fma_f32 v[90:91], v[120:121], v[70:71], v[90:91]
	v_pk_fma_f32 v[158:159], v[124:125], v[2:3], v[158:159]
	v_pk_fma_f32 v[126:127], v[92:93], v[56:57], v[126:127] op_sel:[1,0,0] op_sel_hi:[1,1,1]
	v_pk_fma_f32 v[158:159], v[122:123], v[4:5], v[158:159]
	v_pk_fma_f32 v[124:125], v[92:93], v[58:59], v[124:125] op_sel:[1,0,0] op_sel_hi:[1,1,1]
	v_pk_add_f32 v[156:157], v[156:157], v[90:91]
	v_pk_fma_f32 v[158:159], v[120:121], v[6:7], v[158:159]
	v_add_f32_e32 v155, v156, v157
	v_pk_fma_f32 v[122:123], v[92:93], v[60:61], v[122:123] op_sel:[1,0,0] op_sel_hi:[1,1,1]
	v_pk_fma_f32 v[120:121], v[92:93], v[62:63], v[120:121] op_sel:[1,0,0] op_sel_hi:[1,1,1]
	ds_read_b128 v[0:3], v154 offset:21504
	ds_read_b128 v[4:7], v154 offset:21520
	v_add_f32_e32 v158, v158, v159
	v_add_f32_dpp v155, v155, v155 quad_perm:[1,0,3,2] row_mask:0xf bank_mask:0xf bound_ctrl:1
	s_mov_b32 s6, 0x10101010
	s_mov_b32 s7, 0x10101010
	v_add_f32_dpp v158, v158, v158 quad_perm:[1,0,3,2] row_mask:0xf bank_mask:0xf bound_ctrl:1
	v_add_f32_dpp v155, v155, v155 quad_perm:[2,3,0,1] row_mask:0xf bank_mask:0xf bound_ctrl:1
	s_nop 0
	v_add_f32_dpp v158, v158, v158 quad_perm:[2,3,0,1] row_mask:0xf bank_mask:0xf bound_ctrl:1
	v_add_f32_dpp v156, v155, v155 row_half_mirror row_mask:0xf bank_mask:0xf bound_ctrl:1
	v_pk_fma_f32 v[126:127], v[156:157], v[72:73], v[126:127] op_sel_hi:[0,1,1]
	v_pk_fma_f32 v[124:125], v[156:157], v[74:75], v[124:125] op_sel_hi:[0,1,1]
	v_add_f32_dpp v158, v158, v158 row_half_mirror row_mask:0xf bank_mask:0xf bound_ctrl:1
	v_pk_fma_f32 v[122:123], v[156:157], v[76:77], v[122:123] op_sel_hi:[0,1,1]
	v_pk_fma_f32 v[120:121], v[156:157], v[78:79], v[120:121] op_sel_hi:[0,1,1]
	v_cndmask_b32_e64 v94, v94, v158, s[6:7]
	ds_read_b128 v[64:67], v154 offset:23808
	ds_read_b128 v[68:71], v154 offset:23824
	ds_read_b128 v[56:59], v154 offset:23552
	ds_read_b128 v[60:63], v154 offset:23568
	ds_read_b128 v[72:75], v154 offset:24064
	ds_read_b128 v[76:79], v154 offset:24080
	ds_read_b128 v[48:51], v154 offset:23296
	ds_read_b128 v[52:55], v154 offset:23312
	s_waitcnt lgkmcnt(8)
; #define LAS __attribute__((address_space(3)))
; DI unsigned pack2(float lo, float hi) { f32x2 v = {lo, hi}; return __builtin_bit_cast(unsigned, __builtin_convertvector(v, bf16x2_t)); }
; DI void scan_item(PP p, int l, int item, LAS unsigned char* lds) {
;     ...
;     for (int c = 0; c < NCH; ++c) {
;         if (wid >= 4) { if (c + 1 < NCH) { fill(c + 1); if (c + 2 < NCH) gl(c + 2); } }
;         else {
;             const LAS float* sp = buf + ((c & 1) * T) * 384;
;             f32x4 Ar0, Ar1, Aw0, Aw1, Ak0, Ak1, Aa0, Aa1, Ab0, Ab1; float Avv;
;             f32x4 Br0, Br1, Bw0, Bw1, Bk0, Bk1, Ba0, Ba1, Bb0, Bb1; float Bvv;
;             SC_LD(A, sp);
;             const ptrdiff_t ystep = dir ? -512 : 512;
;             u16* Yl = Yp + (size_t)steprow(b, dir, c * T) * 512 + (ptrdiff_t)ks * ystep;
; #pragma nounroll
;             for (int st = 0; st < T; st += 2) {
;                 SC_LD(B, sp + (st + 1) * 384);
;                 SC_STEP(A, st);
;                 if (st + 2 < T) SC_LD(A, sp + (st + 2) * 384);
;                 SC_STEP(B, st + 1);
;                 if ((st & 6) == 6) {
;                     const LAS float* rp = ypl + (ks * 68 - lane) + (lane & ~7);
;                     const f32x4 q0 = *(const LAS f32x4*)rp, q1 = *(const LAS f32x4*)(rp + 4);
;                     Yl[(ptrdiff_t)(st - 6) * ystep] = (u16)(pack2(((q0[0] + q0[1]) + (q0[2] + q0[3])) + ((q1[0] + q1[1]) + (q1[2] + q1[3])), 0.f) & 0xffffu);
;                 }
	v_pk_mul_f32 v[156:157], v[24:25], v[126:127]
	v_pk_mul_f32 v[90:91], v[28:29], v[122:123]
	v_pk_mul_f32 v[158:159], v[40:41], v[126:127]
	v_pk_fma_f32 v[156:157], v[124:125], v[26:27], v[156:157]
	v_pk_fma_f32 v[90:91], v[120:121], v[30:31], v[90:91]
	v_pk_fma_f32 v[158:159], v[124:125], v[42:43], v[158:159]
	v_pk_fma_f32 v[126:127], v[98:99], v[16:17], v[126:127] op_sel_hi:[0,1,1]
	v_pk_fma_f32 v[158:159], v[122:123], v[44:45], v[158:159]
	v_pk_fma_f32 v[124:125], v[98:99], v[18:19], v[124:125] op_sel_hi:[0,1,1]
	v_pk_add_f32 v[156:157], v[156:157], v[90:91]
	v_pk_fma_f32 v[158:159], v[120:121], v[46:47], v[158:159]
	v_add_f32_e32 v155, v156, v157
	v_pk_fma_f32 v[122:123], v[98:99], v[20:21], v[122:123] op_sel_hi:[0,1,1]
	v_pk_fma_f32 v[120:121], v[98:99], v[22:23], v[120:121] op_sel_hi:[0,1,1]
	ds_read_b128 v[40:43], v154 offset:23040
	ds_read_b128 v[44:47], v154 offset:23056
	v_add_f32_e32 v158, v158, v159
	v_add_f32_dpp v155, v155, v155 quad_perm:[1,0,3,2] row_mask:0xf bank_mask:0xf bound_ctrl:1
	s_mov_b32 s6, 0x20202020
	s_mov_b32 s7, 0x20202020
	v_add_f32_dpp v158, v158, v158 quad_perm:[1,0,3,2] row_mask:0xf bank_mask:0xf bound_ctrl:1
	v_add_f32_dpp v155, v155, v155 quad_perm:[2,3,0,1] row_mask:0xf bank_mask:0xf bound_ctrl:1
	s_nop 0
	v_add_f32_dpp v158, v158, v158 quad_perm:[2,3,0,1] row_mask:0xf bank_mask:0xf bound_ctrl:1
	v_add_f32_dpp v156, v155, v155 row_half_mirror row_mask:0xf bank_mask:0xf bound_ctrl:1
	v_pk_fma_f32 v[126:127], v[156:157], v[32:33], v[126:127] op_sel_hi:[0,1,1]
	v_pk_fma_f32 v[124:125], v[156:157], v[34:35], v[124:125] op_sel_hi:[0,1,1]
	v_add_f32_dpp v158, v158, v158 row_half_mirror row_mask:0xf bank_mask:0xf bound_ctrl:1
	v_pk_fma_f32 v[122:123], v[156:157], v[36:37], v[122:123] op_sel_hi:[0,1,1]
	v_pk_fma_f32 v[120:121], v[156:157], v[38:39], v[120:121] op_sel_hi:[0,1,1]
	v_cndmask_b32_e64 v94, v94, v158, s[6:7]
	ds_read_b128 v[24:27], v154 offset:25344
	ds_read_b128 v[28:31], v154 offset:25360
	ds_read_b128 v[16:19], v154 offset:25088
	ds_read_b128 v[20:23], v154 offset:25104
	ds_read_b128 v[32:35], v154 offset:25600
	ds_read_b128 v[36:39], v154 offset:25616
	ds_read2st64_b32 v[92:93], v153 offset0:101 offset1:107
	s_waitcnt lgkmcnt(7)
	v_pk_mul_f32 v[156:157], v[64:65], v[126:127]
	v_pk_mul_f32 v[90:91], v[68:69], v[122:123]
	v_pk_mul_f32 v[158:159], v[0:1], v[126:127]
	v_pk_fma_f32 v[156:157], v[124:125], v[66:67], v[156:157]
	v_pk_fma_f32 v[90:91], v[120:121], v[70:71], v[90:91]
	v_pk_fma_f32 v[158:159], v[124:125], v[2:3], v[158:159]
	v_pk_fma_f32 v[126:127], v[98:99], v[56:57], v[126:127] op_sel:[1,0,0] op_sel_hi:[1,1,1]
	v_pk_fma_f32 v[158:159], v[122:123], v[4:5], v[158:159]
	v_pk_fma_f32 v[124:125], v[98:99], v[58:59], v[124:125] op_sel:[1,0,0] op_sel_hi:[1,1,1]
	v_pk_add_f32 v[156:157], v[156:157], v[90:91]
	v_pk_fma_f32 v[158:159], v[120:121], v[6:7], v[158:159]
	v_add_f32_e32 v155, v156, v157
	v_pk_fma_f32 v[122:123], v[98:99], v[60:61], v[122:123] op_sel:[1,0,0] op_sel_hi:[1,1,1]
	v_pk_fma_f32 v[120:121], v[98:99], v[62:63], v[120:121] op_sel:[1,0,0] op_sel_hi:[1,1,1]
	ds_read_b128 v[0:3], v154 offset:24576
	ds_read_b128 v[4:7], v154 offset:24592
	v_add_f32_e32 v158, v158, v159
	v_add_f32_dpp v155, v155, v155 quad_perm:[1,0,3,2] row_mask:0xf bank_mask:0xf bound_ctrl:1
	s_mov_b32 s6, 0x40404040
	s_mov_b32 s7, 0x40404040
	v_add_f32_dpp v158, v158, v158 quad_perm:[1,0,3,2] row_mask:0xf bank_mask:0xf bound_ctrl:1
	v_add_f32_dpp v155, v155, v155 quad_perm:[2,3,0,1] row_mask:0xf bank_mask:0xf bound_ctrl:1
	s_nop 0
	v_add_f32_dpp v158, v158, v158 quad_perm:[2,3,0,1] row_mask:0xf bank_mask:0xf bound_ctrl:1
	v_add_f32_dpp v156, v155, v155 row_half_mirror row_mask:0xf bank_mask:0xf bound_ctrl:1
	v_pk_fma_f32 v[126:127], v[156:157], v[72:73], v[126:127] op_sel_hi:[0,1,1]
	v_pk_fma_f32 v[124:125], v[156:157], v[74:75], v[124:125] op_sel_hi:[0,1,1]
	v_add_f32_dpp v158, v158, v158 row_half_mirror row_mask:0xf bank_mask:0xf bound_ctrl:1
	v_pk_fma_f32 v[122:123], v[156:157], v[76:77], v[122:123] op_sel_hi:[0,1,1]
	v_pk_fma_f32 v[120:121], v[156:157], v[78:79], v[120:121] op_sel_hi:[0,1,1]
	v_cndmask_b32_e64 v94, v94, v158, s[6:7]
	v_pk_mul_f32 v[158:159], v[40:41], v[126:127]
	s_nop 0
	v_pk_fma_f32 v[158:159], v[124:125], v[42:43], v[158:159]
	s_nop 0
	v_pk_fma_f32 v[158:159], v[122:123], v[44:45], v[158:159]
	s_nop 0
	v_pk_fma_f32 v[158:159], v[120:121], v[46:47], v[158:159]
	s_nop 0
	v_add_f32_e32 v158, v158, v159
	s_mov_b32 s6, 0x80808080
	s_mov_b32 s7, 0x80808080
	v_add_f32_dpp v158, v158, v158 quad_perm:[1,0,3,2] row_mask:0xf bank_mask:0xf bound_ctrl:1
	s_nop 1
	v_add_f32_dpp v158, v158, v158 quad_perm:[2,3,0,1] row_mask:0xf bank_mask:0xf bound_ctrl:1
	s_nop 1
	v_add_f32_dpp v158, v158, v158 row_half_mirror row_mask:0xf bank_mask:0xf bound_ctrl:1
	v_pk_mul_f32 v[126:127], v[48:49], v[126:127]
	v_pk_mul_f32 v[124:125], v[50:51], v[124:125]
	v_pk_mul_f32 v[122:123], v[52:53], v[122:123]
	v_pk_mul_f32 v[120:121], v[54:55], v[120:121]
	v_cndmask_b32_e64 v94, v94, v158, s[6:7]
	ds_read_b128 v[40:43], v154 offset:26112
	ds_read_b128 v[44:47], v154 offset:26128
	ds_read_b128 v[64:67], v154 offset:26880
	ds_read_b128 v[68:71], v154 offset:26896
	ds_read_b128 v[56:59], v154 offset:26624
	ds_read_b128 v[60:63], v154 offset:26640
	ds_read_b128 v[72:75], v154 offset:27136
	ds_read_b128 v[76:79], v154 offset:27152
	s_waitcnt lgkmcnt(8)
; #define LAS __attribute__((address_space(3)))
; DI unsigned pack2(float lo, float hi) { f32x2 v = {lo, hi}; return __builtin_bit_cast(unsigned, __builtin_convertvector(v, bf16x2_t)); }
; DI void scan_item(PP p, int l, int item, LAS unsigned char* lds) {
;     ...
;     for (int c = 0; c < NCH; ++c) {
;         if (wid >= 4) { if (c + 1 < NCH) { fill(c + 1); if (c + 2 < NCH) gl(c + 2); } }
;         else {
;             const LAS float* sp = buf + ((c & 1) * T) * 384;
;             f32x4 Ar0, Ar1, Aw0, Aw1, Ak0, Ak1, Aa0, Aa1, Ab0, Ab1; float Avv;
;             f32x4 Br0, Br1, Bw0, Bw1, Bk0, Bk1, Ba0, Ba1, Bb0, Bb1; float Bvv;
;             SC_LD(A, sp);
;             const ptrdiff_t ystep = dir ? -512 : 512;
;             u16* Yl = Yp + (size_t)steprow(b, dir, c * T) * 512 + (ptrdiff_t)ks * ystep;
; #pragma nounroll
;             for (int st = 0; st < T; st += 2) {
;                 SC_LD(B, sp + (st + 1) * 384);
;                 SC_STEP(A, st);
;                 if (st + 2 < T) SC_LD(A, sp + (st + 2) * 384);
;                 SC_STEP(B, st + 1);
;                 if ((st & 6) == 6) {
;                     const LAS float* rp = ypl + (ks * 68 - lane) + (lane & ~7);
;                     const f32x4 q0 = *(const LAS f32x4*)rp, q1 = *(const LAS f32x4*)(rp + 4);
;                     Yl[(ptrdiff_t)(st - 6) * ystep] = (u16)(pack2(((q0[0] + q0[1]) + (q0[2] + q0[3])) + ((q1[0] + q1[1]) + (q1[2] + q1[3])), 0.f) & 0xffffu);
;                 }
	v_pk_mul_f32 v[156:157], v[24:25], v[126:127]
	v_pk_mul_f32 v[90:91], v[28:29], v[122:123]
	v_pk_fma_f32 v[126:127], v[92:93], v[16:17], v[126:127] op_sel_hi:[0,1,1]
	v_pk_fma_f32 v[156:157], v[124:125], v[26:27], v[156:157]
	v_pk_fma_f32 v[90:91], v[120:121], v[30:31], v[90:91]
	v_pk_fma_f32 v[124:125], v[92:93], v[18:19], v[124:125] op_sel_hi:[0,1,1]
	v_pk_fma_f32 v[122:123], v[92:93], v[20:21], v[122:123] op_sel_hi:[0,1,1]
	v_pk_add_f32 v[156:157], v[156:157], v[90:91]
	v_pk_fma_f32 v[120:121], v[92:93], v[22:23], v[120:121] op_sel_hi:[0,1,1]
	v_add_f32_e32 v155, v156, v157
	s_nop 1
	v_add_f32_dpp v155, v155, v155 quad_perm:[1,0,3,2] row_mask:0xf bank_mask:0xf bound_ctrl:1
	s_nop 1
	v_add_f32_dpp v155, v155, v155 quad_perm:[2,3,0,1] row_mask:0xf bank_mask:0xf bound_ctrl:1
	s_nop 1
	v_add_f32_dpp v156, v155, v155 row_half_mirror row_mask:0xf bank_mask:0xf bound_ctrl:1
	v_pk_fma_f32 v[126:127], v[156:157], v[32:33], v[126:127] op_sel_hi:[0,1,1]
	v_pk_fma_f32 v[124:125], v[156:157], v[34:35], v[124:125] op_sel_hi:[0,1,1]
	v_pk_fma_f32 v[122:123], v[156:157], v[36:37], v[122:123] op_sel_hi:[0,1,1]
	v_pk_fma_f32 v[120:121], v[156:157], v[38:39], v[120:121] op_sel_hi:[0,1,1]
	v_cvt_pk_bf16_f32 v82, v94, v94
	global_store_short v[118:119], v82, off
	v_lshl_add_u64 v[118:119], s[8:9], 0, v[118:119]
	ds_read_b128 v[24:27], v154 offset:28416
	ds_read_b128 v[28:31], v154 offset:28432
	ds_read_b128 v[16:19], v154 offset:28160
	ds_read_b128 v[20:23], v154 offset:28176
	ds_read_b128 v[32:35], v154 offset:28672
	ds_read_b128 v[36:39], v154 offset:28688
	ds_read2st64_b32 v[98:99], v153 offset0:113 offset1:119
	s_waitcnt lgkmcnt(7)
	v_pk_mul_f32 v[156:157], v[64:65], v[126:127]
	v_pk_mul_f32 v[90:91], v[68:69], v[122:123]
	v_pk_mul_f32 v[158:159], v[0:1], v[126:127]
	v_pk_fma_f32 v[156:157], v[124:125], v[66:67], v[156:157]
	v_pk_fma_f32 v[90:91], v[120:121], v[70:71], v[90:91]
	v_pk_fma_f32 v[158:159], v[124:125], v[2:3], v[158:159]
	v_pk_fma_f32 v[126:127], v[92:93], v[56:57], v[126:127] op_sel:[1,0,0] op_sel_hi:[1,1,1]
	v_pk_fma_f32 v[158:159], v[122:123], v[4:5], v[158:159]
	v_pk_fma_f32 v[124:125], v[92:93], v[58:59], v[124:125] op_sel:[1,0,0] op_sel_hi:[1,1,1]
	v_pk_add_f32 v[156:157], v[156:157], v[90:91]
	v_pk_fma_f32 v[158:159], v[120:121], v[6:7], v[158:159]
	v_add_f32_e32 v155, v156, v157
	v_pk_fma_f32 v[122:123], v[92:93], v[60:61], v[122:123] op_sel:[1,0,0] op_sel_hi:[1,1,1]
	v_pk_fma_f32 v[120:121], v[92:93], v[62:63], v[120:121] op_sel:[1,0,0] op_sel_hi:[1,1,1]
	ds_read_b128 v[0:3], v154 offset:27648
	ds_read_b128 v[4:7], v154 offset:27664
	v_add_f32_e32 v158, v158, v159
	v_add_f32_dpp v155, v155, v155 quad_perm:[1,0,3,2] row_mask:0xf bank_mask:0xf bound_ctrl:1
	s_mov_b32 s6, 0x1010101
	s_mov_b32 s7, 0x1010101
	v_add_f32_dpp v158, v158, v158 quad_perm:[1,0,3,2] row_mask:0xf bank_mask:0xf bound_ctrl:1
	v_add_f32_dpp v155, v155, v155 quad_perm:[2,3,0,1] row_mask:0xf bank_mask:0xf bound_ctrl:1
	s_nop 0
	v_add_f32_dpp v158, v158, v158 quad_perm:[2,3,0,1] row_mask:0xf bank_mask:0xf bound_ctrl:1
	v_add_f32_dpp v156, v155, v155 row_half_mirror row_mask:0xf bank_mask:0xf bound_ctrl:1
	v_pk_fma_f32 v[126:127], v[156:157], v[72:73], v[126:127] op_sel_hi:[0,1,1]
	v_pk_fma_f32 v[124:125], v[156:157], v[74:75], v[124:125] op_sel_hi:[0,1,1]
	v_add_f32_dpp v158, v158, v158 row_half_mirror row_mask:0xf bank_mask:0xf bound_ctrl:1
	v_pk_fma_f32 v[122:123], v[156:157], v[76:77], v[122:123] op_sel_hi:[0,1,1]
	v_pk_fma_f32 v[120:121], v[156:157], v[78:79], v[120:121] op_sel_hi:[0,1,1]
	v_cndmask_b32_e64 v94, v94, v158, s[6:7]
	ds_read_b128 v[64:67], v154 offset:29952
	ds_read_b128 v[68:71], v154 offset:29968
	ds_read_b128 v[56:59], v154 offset:29696
	ds_read_b128 v[60:63], v154 offset:29712
	ds_read_b128 v[72:75], v154 offset:30208
	ds_read_b128 v[76:79], v154 offset:30224
	s_waitcnt lgkmcnt(6)
	v_pk_mul_f32 v[156:157], v[24:25], v[126:127]
	v_pk_mul_f32 v[90:91], v[28:29], v[122:123]
	v_pk_mul_f32 v[158:159], v[40:41], v[126:127]
	v_pk_fma_f32 v[156:157], v[124:125], v[26:27], v[156:157]
	v_pk_fma_f32 v[90:91], v[120:121], v[30:31], v[90:91]
	v_pk_fma_f32 v[158:159], v[124:125], v[42:43], v[158:159]
	v_pk_fma_f32 v[126:127], v[98:99], v[16:17], v[126:127] op_sel_hi:[0,1,1]
	v_pk_fma_f32 v[158:159], v[122:123], v[44:45], v[158:159]
	v_pk_fma_f32 v[124:125], v[98:99], v[18:19], v[124:125] op_sel_hi:[0,1,1]
	v_pk_add_f32 v[156:157], v[156:157], v[90:91]
	v_pk_fma_f32 v[158:159], v[120:121], v[46:47], v[158:159]
	v_add_f32_e32 v155, v156, v157
	v_pk_fma_f32 v[122:123], v[98:99], v[20:21], v[122:123] op_sel_hi:[0,1,1]
	v_pk_fma_f32 v[120:121], v[98:99], v[22:23], v[120:121] op_sel_hi:[0,1,1]
	ds_read_b128 v[40:43], v154 offset:29184
	ds_read_b128 v[44:47], v154 offset:29200
	v_add_f32_e32 v158, v158, v159
	v_add_f32_dpp v155, v155, v155 quad_perm:[1,0,3,2] row_mask:0xf bank_mask:0xf bound_ctrl:1
	s_mov_b32 s6, 0x2020202
	s_mov_b32 s7, 0x2020202
	v_add_f32_dpp v158, v158, v158 quad_perm:[1,0,3,2] row_mask:0xf bank_mask:0xf bound_ctrl:1
	v_add_f32_dpp v155, v155, v155 quad_perm:[2,3,0,1] row_mask:0xf bank_mask:0xf bound_ctrl:1
	s_nop 0
	v_add_f32_dpp v158, v158, v158 quad_perm:[2,3,0,1] row_mask:0xf bank_mask:0xf bound_ctrl:1
	v_add_f32_dpp v156, v155, v155 row_half_mirror row_mask:0xf bank_mask:0xf bound_ctrl:1
	v_pk_fma_f32 v[126:127], v[156:157], v[32:33], v[126:127] op_sel_hi:[0,1,1]
	v_pk_fma_f32 v[124:125], v[156:157], v[34:35], v[124:125] op_sel_hi:[0,1,1]
	v_add_f32_dpp v158, v158, v158 row_half_mirror row_mask:0xf bank_mask:0xf bound_ctrl:1
	v_pk_fma_f32 v[122:123], v[156:157], v[36:37], v[122:123] op_sel_hi:[0,1,1]
	v_pk_fma_f32 v[120:121], v[156:157], v[38:39], v[120:121] op_sel_hi:[0,1,1]
	v_cndmask_b32_e64 v94, v94, v158, s[6:7]
	ds_read_b128 v[24:27], v154 offset:31488
	ds_read_b128 v[28:31], v154 offset:31504
	ds_read_b128 v[16:19], v154 offset:31232
	ds_read_b128 v[20:23], v154 offset:31248
	ds_read_b128 v[32:35], v154 offset:31744
	ds_read_b128 v[36:39], v154 offset:31760
	ds_read2st64_b32 v[92:93], v153 offset0:125 offset1:131
	s_waitcnt lgkmcnt(7)
; #define LAS __attribute__((address_space(3)))
; DI unsigned pack2(float lo, float hi) { f32x2 v = {lo, hi}; return __builtin_bit_cast(unsigned, __builtin_convertvector(v, bf16x2_t)); }
; DI void scan_item(PP p, int l, int item, LAS unsigned char* lds) {
;     ...
;     for (int c = 0; c < NCH; ++c) {
;         if (wid >= 4) { if (c + 1 < NCH) { fill(c + 1); if (c + 2 < NCH) gl(c + 2); } }
;         else {
;             const LAS float* sp = buf + ((c & 1) * T) * 384;
;             f32x4 Ar0, Ar1, Aw0, Aw1, Ak0, Ak1, Aa0, Aa1, Ab0, Ab1; float Avv;
;             f32x4 Br0, Br1, Bw0, Bw1, Bk0, Bk1, Ba0, Ba1, Bb0, Bb1; float Bvv;
;             SC_LD(A, sp);
;             const ptrdiff_t ystep = dir ? -512 : 512;
;             u16* Yl = Yp + (size_t)steprow(b, dir, c * T) * 512 + (ptrdiff_t)ks * ystep;
; #pragma nounroll
;             for (int st = 0; st < T; st += 2) {
;                 SC_LD(B, sp + (st + 1) * 384);
;                 SC_STEP(A, st);
;                 if (st + 2 < T) SC_LD(A, sp + (st + 2) * 384);
;                 SC_STEP(B, st + 1);
;                 if ((st & 6) == 6) {
;                     const LAS float* rp = ypl + (ks * 68 - lane) + (lane & ~7);
;                     const f32x4 q0 = *(const LAS f32x4*)rp, q1 = *(const LAS f32x4*)(rp + 4);
;                     Yl[(ptrdiff_t)(st - 6) * ystep] = (u16)(pack2(((q0[0] + q0[1]) + (q0[2] + q0[3])) + ((q1[0] + q1[1]) + (q1[2] + q1[3])), 0.f) & 0xffffu);
;                 }
	v_pk_mul_f32 v[156:157], v[64:65], v[126:127]
	v_pk_mul_f32 v[90:91], v[68:69], v[122:123]
	v_pk_mul_f32 v[158:159], v[0:1], v[126:127]
	v_pk_fma_f32 v[156:157], v[124:125], v[66:67], v[156:157]
	v_pk_fma_f32 v[90:91], v[120:121], v[70:71], v[90:91]
	v_pk_fma_f32 v[158:159], v[124:125], v[2:3], v[158:159]
	v_pk_fma_f32 v[126:127], v[98:99], v[56:57], v[126:127] op_sel:[1,0,0] op_sel_hi:[1,1,1]
	v_pk_fma_f32 v[158:159], v[122:123], v[4:5], v[158:159]
	v_pk_fma_f32 v[124:125], v[98:99], v[58:59], v[124:125] op_sel:[1,0,0] op_sel_hi:[1,1,1]
	v_pk_add_f32 v[156:157], v[156:157], v[90:91]
	v_pk_fma_f32 v[158:159], v[120:121], v[6:7], v[158:159]
	v_add_f32_e32 v155, v156, v157
	v_pk_fma_f32 v[122:123], v[98:99], v[60:61], v[122:123] op_sel:[1,0,0] op_sel_hi:[1,1,1]
	v_pk_fma_f32 v[120:121], v[98:99], v[62:63], v[120:121] op_sel:[1,0,0] op_sel_hi:[1,1,1]
	ds_read_b128 v[0:3], v154 offset:30720
	ds_read_b128 v[4:7], v154 offset:30736
	v_add_f32_e32 v158, v158, v159
	v_add_f32_dpp v155, v155, v155 quad_perm:[1,0,3,2] row_mask:0xf bank_mask:0xf bound_ctrl:1
	s_mov_b32 s6, 0x4040404
	s_mov_b32 s7, 0x4040404
	v_add_f32_dpp v158, v158, v158 quad_perm:[1,0,3,2] row_mask:0xf bank_mask:0xf bound_ctrl:1
	v_add_f32_dpp v155, v155, v155 quad_perm:[2,3,0,1] row_mask:0xf bank_mask:0xf bound_ctrl:1
	s_nop 0
	v_add_f32_dpp v158, v158, v158 quad_perm:[2,3,0,1] row_mask:0xf bank_mask:0xf bound_ctrl:1
	v_add_f32_dpp v156, v155, v155 row_half_mirror row_mask:0xf bank_mask:0xf bound_ctrl:1
	v_pk_fma_f32 v[126:127], v[156:157], v[72:73], v[126:127] op_sel_hi:[0,1,1]
	v_pk_fma_f32 v[124:125], v[156:157], v[74:75], v[124:125] op_sel_hi:[0,1,1]
	v_add_f32_dpp v158, v158, v158 row_half_mirror row_mask:0xf bank_mask:0xf bound_ctrl:1
	v_pk_fma_f32 v[122:123], v[156:157], v[76:77], v[122:123] op_sel_hi:[0,1,1]
	v_pk_fma_f32 v[120:121], v[156:157], v[78:79], v[120:121] op_sel_hi:[0,1,1]
	v_cndmask_b32_e64 v94, v94, v158, s[6:7]
	ds_read_b128 v[64:67], v154 offset:33024
	ds_read_b128 v[68:71], v154 offset:33040
	ds_read_b128 v[56:59], v154 offset:32768
	ds_read_b128 v[60:63], v154 offset:32784
	ds_read_b128 v[72:75], v154 offset:33280
	ds_read_b128 v[76:79], v154 offset:33296
	s_waitcnt lgkmcnt(6)
	v_pk_mul_f32 v[156:157], v[24:25], v[126:127]
	v_pk_mul_f32 v[90:91], v[28:29], v[122:123]
	v_pk_mul_f32 v[158:159], v[40:41], v[126:127]
	v_pk_fma_f32 v[156:157], v[124:125], v[26:27], v[156:157]
	v_pk_fma_f32 v[90:91], v[120:121], v[30:31], v[90:91]
	v_pk_fma_f32 v[158:159], v[124:125], v[42:43], v[158:159]
	v_pk_fma_f32 v[126:127], v[92:93], v[16:17], v[126:127] op_sel_hi:[0,1,1]
	v_pk_fma_f32 v[158:159], v[122:123], v[44:45], v[158:159]
	v_pk_fma_f32 v[124:125], v[92:93], v[18:19], v[124:125] op_sel_hi:[0,1,1]
	v_pk_add_f32 v[156:157], v[156:157], v[90:91]
	v_pk_fma_f32 v[158:159], v[120:121], v[46:47], v[158:159]
	v_add_f32_e32 v155, v156, v157
	v_pk_fma_f32 v[122:123], v[92:93], v[20:21], v[122:123] op_sel_hi:[0,1,1]
	v_pk_fma_f32 v[120:121], v[92:93], v[22:23], v[120:121] op_sel_hi:[0,1,1]
	ds_read_b128 v[40:43], v154 offset:32256
	ds_read_b128 v[44:47], v154 offset:32272
	v_add_f32_e32 v158, v158, v159
	v_add_f32_dpp v155, v155, v155 quad_perm:[1,0,3,2] row_mask:0xf bank_mask:0xf bound_ctrl:1
	s_mov_b32 s6, 0x8080808
	s_mov_b32 s7, 0x8080808
	v_add_f32_dpp v158, v158, v158 quad_perm:[1,0,3,2] row_mask:0xf bank_mask:0xf bound_ctrl:1
	v_add_f32_dpp v155, v155, v155 quad_perm:[2,3,0,1] row_mask:0xf bank_mask:0xf bound_ctrl:1
	s_nop 0
	v_add_f32_dpp v158, v158, v158 quad_perm:[2,3,0,1] row_mask:0xf bank_mask:0xf bound_ctrl:1
	v_add_f32_dpp v156, v155, v155 row_half_mirror row_mask:0xf bank_mask:0xf bound_ctrl:1
	v_pk_fma_f32 v[126:127], v[156:157], v[32:33], v[126:127] op_sel_hi:[0,1,1]
	v_pk_fma_f32 v[124:125], v[156:157], v[34:35], v[124:125] op_sel_hi:[0,1,1]
	v_add_f32_dpp v158, v158, v158 row_half_mirror row_mask:0xf bank_mask:0xf bound_ctrl:1
	v_pk_fma_f32 v[122:123], v[156:157], v[36:37], v[122:123] op_sel_hi:[0,1,1]
	v_pk_fma_f32 v[120:121], v[156:157], v[38:39], v[120:121] op_sel_hi:[0,1,1]
	v_cndmask_b32_e64 v94, v94, v158, s[6:7]
	ds_read_b128 v[24:27], v154 offset:34560
	ds_read_b128 v[28:31], v154 offset:34576
	ds_read_b128 v[16:19], v154 offset:34304
	ds_read_b128 v[20:23], v154 offset:34320
	ds_read_b128 v[32:35], v154 offset:34816
	ds_read_b128 v[36:39], v154 offset:34832
	ds_read2st64_b32 v[98:99], v153 offset0:137 offset1:143
	s_waitcnt lgkmcnt(7)
	v_pk_mul_f32 v[156:157], v[64:65], v[126:127]
	v_pk_mul_f32 v[90:91], v[68:69], v[122:123]
	v_pk_mul_f32 v[158:159], v[0:1], v[126:127]
	v_pk_fma_f32 v[156:157], v[124:125], v[66:67], v[156:157]
	v_pk_fma_f32 v[90:91], v[120:121], v[70:71], v[90:91]
	v_pk_fma_f32 v[158:159], v[124:125], v[2:3], v[158:159]
	v_pk_fma_f32 v[126:127], v[92:93], v[56:57], v[126:127] op_sel:[1,0,0] op_sel_hi:[1,1,1]
	v_pk_fma_f32 v[158:159], v[122:123], v[4:5], v[158:159]
	v_pk_fma_f32 v[124:125], v[92:93], v[58:59], v[124:125] op_sel:[1,0,0] op_sel_hi:[1,1,1]
	v_pk_add_f32 v[156:157], v[156:157], v[90:91]
	v_pk_fma_f32 v[158:159], v[120:121], v[6:7], v[158:159]
	v_add_f32_e32 v155, v156, v157
	v_pk_fma_f32 v[122:123], v[92:93], v[60:61], v[122:123] op_sel:[1,0,0] op_sel_hi:[1,1,1]
	v_pk_fma_f32 v[120:121], v[92:93], v[62:63], v[120:121] op_sel:[1,0,0] op_sel_hi:[1,1,1]
	ds_read_b128 v[0:3], v154 offset:33792
	ds_read_b128 v[4:7], v154 offset:33808
	v_add_f32_e32 v158, v158, v159
	v_add_f32_dpp v155, v155, v155 quad_perm:[1,0,3,2] row_mask:0xf bank_mask:0xf bound_ctrl:1
	s_mov_b32 s6, 0x10101010
	s_mov_b32 s7, 0x10101010
	v_add_f32_dpp v158, v158, v158 quad_perm:[1,0,3,2] row_mask:0xf bank_mask:0xf bound_ctrl:1
	v_add_f32_dpp v155, v155, v155 quad_perm:[2,3,0,1] row_mask:0xf bank_mask:0xf bound_ctrl:1
	s_nop 0
	v_add_f32_dpp v158, v158, v158 quad_perm:[2,3,0,1] row_mask:0xf bank_mask:0xf bound_ctrl:1
	v_add_f32_dpp v156, v155, v155 row_half_mirror row_mask:0xf bank_mask:0xf bound_ctrl:1
	v_pk_fma_f32 v[126:127], v[156:157], v[72:73], v[126:127] op_sel_hi:[0,1,1]
	v_pk_fma_f32 v[124:125], v[156:157], v[74:75], v[124:125] op_sel_hi:[0,1,1]
	v_add_f32_dpp v158, v158, v158 row_half_mirror row_mask:0xf bank_mask:0xf bound_ctrl:1
	v_pk_fma_f32 v[122:123], v[156:157], v[76:77], v[122:123] op_sel_hi:[0,1,1]
	v_pk_fma_f32 v[120:121], v[156:157], v[78:79], v[120:121] op_sel_hi:[0,1,1]
	v_cndmask_b32_e64 v94, v94, v158, s[6:7]
	ds_read_b128 v[64:67], v154 offset:36096
	ds_read_b128 v[68:71], v154 offset:36112
	ds_read_b128 v[56:59], v154 offset:35840
	ds_read_b128 v[60:63], v154 offset:35856
	ds_read_b128 v[72:75], v154 offset:36352
	ds_read_b128 v[76:79], v154 offset:36368
	ds_read_b128 v[48:51], v154 offset:35584
	ds_read_b128 v[52:55], v154 offset:35600
	s_waitcnt lgkmcnt(8)
; #define LAS __attribute__((address_space(3)))
; DI unsigned pack2(float lo, float hi) { f32x2 v = {lo, hi}; return __builtin_bit_cast(unsigned, __builtin_convertvector(v, bf16x2_t)); }
; DI void scan_item(PP p, int l, int item, LAS unsigned char* lds) {
;     ...
;     for (int c = 0; c < NCH; ++c) {
;         if (wid >= 4) { if (c + 1 < NCH) { fill(c + 1); if (c + 2 < NCH) gl(c + 2); } }
;         else {
;             const LAS float* sp = buf + ((c & 1) * T) * 384;
;             f32x4 Ar0, Ar1, Aw0, Aw1, Ak0, Ak1, Aa0, Aa1, Ab0, Ab1; float Avv;
;             f32x4 Br0, Br1, Bw0, Bw1, Bk0, Bk1, Ba0, Ba1, Bb0, Bb1; float Bvv;
;             SC_LD(A, sp);
;             const ptrdiff_t ystep = dir ? -512 : 512;
;             u16* Yl = Yp + (size_t)steprow(b, dir, c * T) * 512 + (ptrdiff_t)ks * ystep;
; #pragma nounroll
;             for (int st = 0; st < T; st += 2) {
;                 SC_LD(B, sp + (st + 1) * 384);
;                 SC_STEP(A, st);
;                 if (st + 2 < T) SC_LD(A, sp + (st + 2) * 384);
;                 SC_STEP(B, st + 1);
;                 if ((st & 6) == 6) {
;                     const LAS float* rp = ypl + (ks * 68 - lane) + (lane & ~7);
;                     const f32x4 q0 = *(const LAS f32x4*)rp, q1 = *(const LAS f32x4*)(rp + 4);
;                     Yl[(ptrdiff_t)(st - 6) * ystep] = (u16)(pack2(((q0[0] + q0[1]) + (q0[2] + q0[3])) + ((q1[0] + q1[1]) + (q1[2] + q1[3])), 0.f) & 0xffffu);
;                 }
	v_pk_mul_f32 v[156:157], v[24:25], v[126:127]
	v_pk_mul_f32 v[90:91], v[28:29], v[122:123]
	v_pk_mul_f32 v[158:159], v[40:41], v[126:127]
	v_pk_fma_f32 v[156:157], v[124:125], v[26:27], v[156:157]
	v_pk_fma_f32 v[90:91], v[120:121], v[30:31], v[90:91]
	v_pk_fma_f32 v[158:159], v[124:125], v[42:43], v[158:159]
	v_pk_fma_f32 v[126:127], v[98:99], v[16:17], v[126:127] op_sel_hi:[0,1,1]
	v_pk_fma_f32 v[158:159], v[122:123], v[44:45], v[158:159]
	v_pk_fma_f32 v[124:125], v[98:99], v[18:19], v[124:125] op_sel_hi:[0,1,1]
	v_pk_add_f32 v[156:157], v[156:157], v[90:91]
	v_pk_fma_f32 v[158:159], v[120:121], v[46:47], v[158:159]
	v_add_f32_e32 v155, v156, v157
	v_pk_fma_f32 v[122:123], v[98:99], v[20:21], v[122:123] op_sel_hi:[0,1,1]
	v_pk_fma_f32 v[120:121], v[98:99], v[22:23], v[120:121] op_sel_hi:[0,1,1]
	ds_read_b128 v[40:43], v154 offset:35328
	ds_read_b128 v[44:47], v154 offset:35344
	v_add_f32_e32 v158, v158, v159
	v_add_f32_dpp v155, v155, v155 quad_perm:[1,0,3,2] row_mask:0xf bank_mask:0xf bound_ctrl:1
	s_mov_b32 s6, 0x20202020
	s_mov_b32 s7, 0x20202020
	v_add_f32_dpp v158, v158, v158 quad_perm:[1,0,3,2] row_mask:0xf bank_mask:0xf bound_ctrl:1
	v_add_f32_dpp v155, v155, v155 quad_perm:[2,3,0,1] row_mask:0xf bank_mask:0xf bound_ctrl:1
	s_nop 0
	v_add_f32_dpp v158, v158, v158 quad_perm:[2,3,0,1] row_mask:0xf bank_mask:0xf bound_ctrl:1
	v_add_f32_dpp v156, v155, v155 row_half_mirror row_mask:0xf bank_mask:0xf bound_ctrl:1
	v_pk_fma_f32 v[126:127], v[156:157], v[32:33], v[126:127] op_sel_hi:[0,1,1]
	v_pk_fma_f32 v[124:125], v[156:157], v[34:35], v[124:125] op_sel_hi:[0,1,1]
	v_add_f32_dpp v158, v158, v158 row_half_mirror row_mask:0xf bank_mask:0xf bound_ctrl:1
	v_pk_fma_f32 v[122:123], v[156:157], v[36:37], v[122:123] op_sel_hi:[0,1,1]
	v_pk_fma_f32 v[120:121], v[156:157], v[38:39], v[120:121] op_sel_hi:[0,1,1]
	v_cndmask_b32_e64 v94, v94, v158, s[6:7]
	ds_read_b128 v[24:27], v154 offset:37632
	ds_read_b128 v[28:31], v154 offset:37648
	ds_read_b128 v[16:19], v154 offset:37376
	ds_read_b128 v[20:23], v154 offset:37392
	ds_read_b128 v[32:35], v154 offset:37888
	ds_read_b128 v[36:39], v154 offset:37904
	ds_read2st64_b32 v[92:93], v153 offset0:149 offset1:155
	s_waitcnt lgkmcnt(7)
	v_pk_mul_f32 v[156:157], v[64:65], v[126:127]
	v_pk_mul_f32 v[90:91], v[68:69], v[122:123]
	v_pk_mul_f32 v[158:159], v[0:1], v[126:127]
	v_pk_fma_f32 v[156:157], v[124:125], v[66:67], v[156:157]
	v_pk_fma_f32 v[90:91], v[120:121], v[70:71], v[90:91]
	v_pk_fma_f32 v[158:159], v[124:125], v[2:3], v[158:159]
	v_pk_fma_f32 v[126:127], v[98:99], v[56:57], v[126:127] op_sel:[1,0,0] op_sel_hi:[1,1,1]
	v_pk_fma_f32 v[158:159], v[122:123], v[4:5], v[158:159]
	v_pk_fma_f32 v[124:125], v[98:99], v[58:59], v[124:125] op_sel:[1,0,0] op_sel_hi:[1,1,1]
	v_pk_add_f32 v[156:157], v[156:157], v[90:91]
	v_pk_fma_f32 v[158:159], v[120:121], v[6:7], v[158:159]
	v_add_f32_e32 v155, v156, v157
	v_pk_fma_f32 v[122:123], v[98:99], v[60:61], v[122:123] op_sel:[1,0,0] op_sel_hi:[1,1,1]
	v_pk_fma_f32 v[120:121], v[98:99], v[62:63], v[120:121] op_sel:[1,0,0] op_sel_hi:[1,1,1]
	ds_read_b128 v[0:3], v154 offset:36864
	ds_read_b128 v[4:7], v154 offset:36880
	v_add_f32_e32 v158, v158, v159
	v_add_f32_dpp v155, v155, v155 quad_perm:[1,0,3,2] row_mask:0xf bank_mask:0xf bound_ctrl:1
	s_mov_b32 s6, 0x40404040
	s_mov_b32 s7, 0x40404040
	v_add_f32_dpp v158, v158, v158 quad_perm:[1,0,3,2] row_mask:0xf bank_mask:0xf bound_ctrl:1
	v_add_f32_dpp v155, v155, v155 quad_perm:[2,3,0,1] row_mask:0xf bank_mask:0xf bound_ctrl:1
	s_nop 0
	v_add_f32_dpp v158, v158, v158 quad_perm:[2,3,0,1] row_mask:0xf bank_mask:0xf bound_ctrl:1
	v_add_f32_dpp v156, v155, v155 row_half_mirror row_mask:0xf bank_mask:0xf bound_ctrl:1
	v_pk_fma_f32 v[126:127], v[156:157], v[72:73], v[126:127] op_sel_hi:[0,1,1]
	v_pk_fma_f32 v[124:125], v[156:157], v[74:75], v[124:125] op_sel_hi:[0,1,1]
	v_add_f32_dpp v158, v158, v158 row_half_mirror row_mask:0xf bank_mask:0xf bound_ctrl:1
	v_pk_fma_f32 v[122:123], v[156:157], v[76:77], v[122:123] op_sel_hi:[0,1,1]
	v_pk_fma_f32 v[120:121], v[156:157], v[78:79], v[120:121] op_sel_hi:[0,1,1]
	v_cndmask_b32_e64 v94, v94, v158, s[6:7]
	v_pk_mul_f32 v[158:159], v[40:41], v[126:127]
	s_nop 0
	v_pk_fma_f32 v[158:159], v[124:125], v[42:43], v[158:159]
	s_nop 0
	v_pk_fma_f32 v[158:159], v[122:123], v[44:45], v[158:159]
	s_nop 0
	v_pk_fma_f32 v[158:159], v[120:121], v[46:47], v[158:159]
	s_nop 0
	v_add_f32_e32 v158, v158, v159
	s_mov_b32 s6, 0x80808080
	s_mov_b32 s7, 0x80808080
	v_add_f32_dpp v158, v158, v158 quad_perm:[1,0,3,2] row_mask:0xf bank_mask:0xf bound_ctrl:1
	s_nop 1
	v_add_f32_dpp v158, v158, v158 quad_perm:[2,3,0,1] row_mask:0xf bank_mask:0xf bound_ctrl:1
	s_nop 1
	v_add_f32_dpp v158, v158, v158 row_half_mirror row_mask:0xf bank_mask:0xf bound_ctrl:1
	v_pk_mul_f32 v[126:127], v[48:49], v[126:127]
	v_pk_mul_f32 v[124:125], v[50:51], v[124:125]
	v_pk_mul_f32 v[122:123], v[52:53], v[122:123]
	v_pk_mul_f32 v[120:121], v[54:55], v[120:121]
	v_cndmask_b32_e64 v94, v94, v158, s[6:7]
	ds_read_b128 v[40:43], v154 offset:38400
	ds_read_b128 v[44:47], v154 offset:38416
	ds_read_b128 v[64:67], v154 offset:39168
	ds_read_b128 v[68:71], v154 offset:39184
	ds_read_b128 v[56:59], v154 offset:38912
	ds_read_b128 v[60:63], v154 offset:38928
	ds_read_b128 v[72:75], v154 offset:39424
	ds_read_b128 v[76:79], v154 offset:39440
	s_waitcnt lgkmcnt(8)
; #define LAS __attribute__((address_space(3)))
; DI unsigned pack2(float lo, float hi) { f32x2 v = {lo, hi}; return __builtin_bit_cast(unsigned, __builtin_convertvector(v, bf16x2_t)); }
; DI void scan_item(PP p, int l, int item, LAS unsigned char* lds) {
;     ...
;     for (int c = 0; c < NCH; ++c) {
;         if (wid >= 4) { if (c + 1 < NCH) { fill(c + 1); if (c + 2 < NCH) gl(c + 2); } }
;         else {
;             const LAS float* sp = buf + ((c & 1) * T) * 384;
;             f32x4 Ar0, Ar1, Aw0, Aw1, Ak0, Ak1, Aa0, Aa1, Ab0, Ab1; float Avv;
;             f32x4 Br0, Br1, Bw0, Bw1, Bk0, Bk1, Ba0, Ba1, Bb0, Bb1; float Bvv;
;             SC_LD(A, sp);
;             const ptrdiff_t ystep = dir ? -512 : 512;
;             u16* Yl = Yp + (size_t)steprow(b, dir, c * T) * 512 + (ptrdiff_t)ks * ystep;
; #pragma nounroll
;             for (int st = 0; st < T; st += 2) {
;                 SC_LD(B, sp + (st + 1) * 384);
;                 SC_STEP(A, st);
;                 if (st + 2 < T) SC_LD(A, sp + (st + 2) * 384);
;                 SC_STEP(B, st + 1);
;                 if ((st & 6) == 6) {
;                     const LAS float* rp = ypl + (ks * 68 - lane) + (lane & ~7);
;                     const f32x4 q0 = *(const LAS f32x4*)rp, q1 = *(const LAS f32x4*)(rp + 4);
;                     Yl[(ptrdiff_t)(st - 6) * ystep] = (u16)(pack2(((q0[0] + q0[1]) + (q0[2] + q0[3])) + ((q1[0] + q1[1]) + (q1[2] + q1[3])), 0.f) & 0xffffu);
;                 }
	v_pk_mul_f32 v[156:157], v[24:25], v[126:127]
	v_pk_mul_f32 v[90:91], v[28:29], v[122:123]
	v_pk_fma_f32 v[126:127], v[92:93], v[16:17], v[126:127] op_sel_hi:[0,1,1]
	v_pk_fma_f32 v[156:157], v[124:125], v[26:27], v[156:157]
	v_pk_fma_f32 v[90:91], v[120:121], v[30:31], v[90:91]
	v_pk_fma_f32 v[124:125], v[92:93], v[18:19], v[124:125] op_sel_hi:[0,1,1]
	v_pk_fma_f32 v[122:123], v[92:93], v[20:21], v[122:123] op_sel_hi:[0,1,1]
	v_pk_add_f32 v[156:157], v[156:157], v[90:91]
	v_pk_fma_f32 v[120:121], v[92:93], v[22:23], v[120:121] op_sel_hi:[0,1,1]
	v_add_f32_e32 v155, v156, v157
	s_nop 1
	v_add_f32_dpp v155, v155, v155 quad_perm:[1,0,3,2] row_mask:0xf bank_mask:0xf bound_ctrl:1
	s_nop 1
	v_add_f32_dpp v155, v155, v155 quad_perm:[2,3,0,1] row_mask:0xf bank_mask:0xf bound_ctrl:1
	s_nop 1
	v_add_f32_dpp v156, v155, v155 row_half_mirror row_mask:0xf bank_mask:0xf bound_ctrl:1
	v_pk_fma_f32 v[126:127], v[156:157], v[32:33], v[126:127] op_sel_hi:[0,1,1]
	v_pk_fma_f32 v[124:125], v[156:157], v[34:35], v[124:125] op_sel_hi:[0,1,1]
	v_pk_fma_f32 v[122:123], v[156:157], v[36:37], v[122:123] op_sel_hi:[0,1,1]
	v_pk_fma_f32 v[120:121], v[156:157], v[38:39], v[120:121] op_sel_hi:[0,1,1]
	v_cvt_pk_bf16_f32 v82, v94, v94
	global_store_short v[118:119], v82, off
	v_lshl_add_u64 v[118:119], s[8:9], 0, v[118:119]
	ds_read_b128 v[24:27], v154 offset:40704
	ds_read_b128 v[28:31], v154 offset:40720
	ds_read_b128 v[16:19], v154 offset:40448
	ds_read_b128 v[20:23], v154 offset:40464
	ds_read_b128 v[32:35], v154 offset:40960
	ds_read_b128 v[36:39], v154 offset:40976
	ds_read2st64_b32 v[98:99], v153 offset0:161 offset1:167
	s_waitcnt lgkmcnt(7)
	v_pk_mul_f32 v[156:157], v[64:65], v[126:127]
	v_pk_mul_f32 v[90:91], v[68:69], v[122:123]
	v_pk_mul_f32 v[158:159], v[0:1], v[126:127]
	v_pk_fma_f32 v[156:157], v[124:125], v[66:67], v[156:157]
	v_pk_fma_f32 v[90:91], v[120:121], v[70:71], v[90:91]
	v_pk_fma_f32 v[158:159], v[124:125], v[2:3], v[158:159]
	v_pk_fma_f32 v[126:127], v[92:93], v[56:57], v[126:127] op_sel:[1,0,0] op_sel_hi:[1,1,1]
	v_pk_fma_f32 v[158:159], v[122:123], v[4:5], v[158:159]
	v_pk_fma_f32 v[124:125], v[92:93], v[58:59], v[124:125] op_sel:[1,0,0] op_sel_hi:[1,1,1]
	v_pk_add_f32 v[156:157], v[156:157], v[90:91]
	v_pk_fma_f32 v[158:159], v[120:121], v[6:7], v[158:159]
	v_add_f32_e32 v155, v156, v157
	v_pk_fma_f32 v[122:123], v[92:93], v[60:61], v[122:123] op_sel:[1,0,0] op_sel_hi:[1,1,1]
	v_pk_fma_f32 v[120:121], v[92:93], v[62:63], v[120:121] op_sel:[1,0,0] op_sel_hi:[1,1,1]
	ds_read_b128 v[0:3], v154 offset:39936
	ds_read_b128 v[4:7], v154 offset:39952
	v_add_f32_e32 v158, v158, v159
	v_add_f32_dpp v155, v155, v155 quad_perm:[1,0,3,2] row_mask:0xf bank_mask:0xf bound_ctrl:1
	s_mov_b32 s6, 0x1010101
	s_mov_b32 s7, 0x1010101
	v_add_f32_dpp v158, v158, v158 quad_perm:[1,0,3,2] row_mask:0xf bank_mask:0xf bound_ctrl:1
	v_add_f32_dpp v155, v155, v155 quad_perm:[2,3,0,1] row_mask:0xf bank_mask:0xf bound_ctrl:1
	s_nop 0
	v_add_f32_dpp v158, v158, v158 quad_perm:[2,3,0,1] row_mask:0xf bank_mask:0xf bound_ctrl:1
	v_add_f32_dpp v156, v155, v155 row_half_mirror row_mask:0xf bank_mask:0xf bound_ctrl:1
	v_pk_fma_f32 v[126:127], v[156:157], v[72:73], v[126:127] op_sel_hi:[0,1,1]
	v_pk_fma_f32 v[124:125], v[156:157], v[74:75], v[124:125] op_sel_hi:[0,1,1]
	v_add_f32_dpp v158, v158, v158 row_half_mirror row_mask:0xf bank_mask:0xf bound_ctrl:1
	v_pk_fma_f32 v[122:123], v[156:157], v[76:77], v[122:123] op_sel_hi:[0,1,1]
	v_pk_fma_f32 v[120:121], v[156:157], v[78:79], v[120:121] op_sel_hi:[0,1,1]
	v_cndmask_b32_e64 v94, v94, v158, s[6:7]
	ds_read_b128 v[64:67], v154 offset:42240
	ds_read_b128 v[68:71], v154 offset:42256
	ds_read_b128 v[56:59], v154 offset:41984
	ds_read_b128 v[60:63], v154 offset:42000
	ds_read_b128 v[72:75], v154 offset:42496
	ds_read_b128 v[76:79], v154 offset:42512
	s_waitcnt lgkmcnt(6)
	v_pk_mul_f32 v[156:157], v[24:25], v[126:127]
	v_pk_mul_f32 v[90:91], v[28:29], v[122:123]
	v_pk_mul_f32 v[158:159], v[40:41], v[126:127]
	v_pk_fma_f32 v[156:157], v[124:125], v[26:27], v[156:157]
	v_pk_fma_f32 v[90:91], v[120:121], v[30:31], v[90:91]
	v_pk_fma_f32 v[158:159], v[124:125], v[42:43], v[158:159]
	v_pk_fma_f32 v[126:127], v[98:99], v[16:17], v[126:127] op_sel_hi:[0,1,1]
	v_pk_fma_f32 v[158:159], v[122:123], v[44:45], v[158:159]
	v_pk_fma_f32 v[124:125], v[98:99], v[18:19], v[124:125] op_sel_hi:[0,1,1]
	v_pk_add_f32 v[156:157], v[156:157], v[90:91]
	v_pk_fma_f32 v[158:159], v[120:121], v[46:47], v[158:159]
	v_add_f32_e32 v155, v156, v157
	v_pk_fma_f32 v[122:123], v[98:99], v[20:21], v[122:123] op_sel_hi:[0,1,1]
	v_pk_fma_f32 v[120:121], v[98:99], v[22:23], v[120:121] op_sel_hi:[0,1,1]
	ds_read_b128 v[40:43], v154 offset:41472
	ds_read_b128 v[44:47], v154 offset:41488
	v_add_f32_e32 v158, v158, v159
	v_add_f32_dpp v155, v155, v155 quad_perm:[1,0,3,2] row_mask:0xf bank_mask:0xf bound_ctrl:1
	s_mov_b32 s6, 0x2020202
	s_mov_b32 s7, 0x2020202
	v_add_f32_dpp v158, v158, v158 quad_perm:[1,0,3,2] row_mask:0xf bank_mask:0xf bound_ctrl:1
	v_add_f32_dpp v155, v155, v155 quad_perm:[2,3,0,1] row_mask:0xf bank_mask:0xf bound_ctrl:1
	s_nop 0
	v_add_f32_dpp v158, v158, v158 quad_perm:[2,3,0,1] row_mask:0xf bank_mask:0xf bound_ctrl:1
	v_add_f32_dpp v156, v155, v155 row_half_mirror row_mask:0xf bank_mask:0xf bound_ctrl:1
	v_pk_fma_f32 v[126:127], v[156:157], v[32:33], v[126:127] op_sel_hi:[0,1,1]
	v_pk_fma_f32 v[124:125], v[156:157], v[34:35], v[124:125] op_sel_hi:[0,1,1]
	v_add_f32_dpp v158, v158, v158 row_half_mirror row_mask:0xf bank_mask:0xf bound_ctrl:1
	v_pk_fma_f32 v[122:123], v[156:157], v[36:37], v[122:123] op_sel_hi:[0,1,1]
	v_pk_fma_f32 v[120:121], v[156:157], v[38:39], v[120:121] op_sel_hi:[0,1,1]
	v_cndmask_b32_e64 v94, v94, v158, s[6:7]
	ds_read_b128 v[24:27], v154 offset:43776
	ds_read_b128 v[28:31], v154 offset:43792
	ds_read_b128 v[16:19], v154 offset:43520
	ds_read_b128 v[20:23], v154 offset:43536
	ds_read_b128 v[32:35], v154 offset:44032
	ds_read_b128 v[36:39], v154 offset:44048
	ds_read2st64_b32 v[92:93], v153 offset0:173 offset1:179
	s_waitcnt lgkmcnt(7)
; #define LAS __attribute__((address_space(3)))
; DI unsigned pack2(float lo, float hi) { f32x2 v = {lo, hi}; return __builtin_bit_cast(unsigned, __builtin_convertvector(v, bf16x2_t)); }
; DI void scan_item(PP p, int l, int item, LAS unsigned char* lds) {
;     ...
;     for (int c = 0; c < NCH; ++c) {
;         if (wid >= 4) { if (c + 1 < NCH) { fill(c + 1); if (c + 2 < NCH) gl(c + 2); } }
;         else {
;             const LAS float* sp = buf + ((c & 1) * T) * 384;
;             f32x4 Ar0, Ar1, Aw0, Aw1, Ak0, Ak1, Aa0, Aa1, Ab0, Ab1; float Avv;
;             f32x4 Br0, Br1, Bw0, Bw1, Bk0, Bk1, Ba0, Ba1, Bb0, Bb1; float Bvv;
;             SC_LD(A, sp);
;             const ptrdiff_t ystep = dir ? -512 : 512;
;             u16* Yl = Yp + (size_t)steprow(b, dir, c * T) * 512 + (ptrdiff_t)ks * ystep;
; #pragma nounroll
;             for (int st = 0; st < T; st += 2) {
;                 SC_LD(B, sp + (st + 1) * 384);
;                 SC_STEP(A, st);
;                 if (st + 2 < T) SC_LD(A, sp + (st + 2) * 384);
;                 SC_STEP(B, st + 1);
;                 if ((st & 6) == 6) {
;                     const LAS float* rp = ypl + (ks * 68 - lane) + (lane & ~7);
;                     const f32x4 q0 = *(const LAS f32x4*)rp, q1 = *(const LAS f32x4*)(rp + 4);
;                     Yl[(ptrdiff_t)(st - 6) * ystep] = (u16)(pack2(((q0[0] + q0[1]) + (q0[2] + q0[3])) + ((q1[0] + q1[1]) + (q1[2] + q1[3])), 0.f) & 0xffffu);
;                 }
	v_pk_mul_f32 v[156:157], v[64:65], v[126:127]
	v_pk_mul_f32 v[90:91], v[68:69], v[122:123]
	v_pk_mul_f32 v[158:159], v[0:1], v[126:127]
	v_pk_fma_f32 v[156:157], v[124:125], v[66:67], v[156:157]
	v_pk_fma_f32 v[90:91], v[120:121], v[70:71], v[90:91]
	v_pk_fma_f32 v[158:159], v[124:125], v[2:3], v[158:159]
	v_pk_fma_f32 v[126:127], v[98:99], v[56:57], v[126:127] op_sel:[1,0,0] op_sel_hi:[1,1,1]
	v_pk_fma_f32 v[158:159], v[122:123], v[4:5], v[158:159]
	v_pk_fma_f32 v[124:125], v[98:99], v[58:59], v[124:125] op_sel:[1,0,0] op_sel_hi:[1,1,1]
	v_pk_add_f32 v[156:157], v[156:157], v[90:91]
	v_pk_fma_f32 v[158:159], v[120:121], v[6:7], v[158:159]
	v_add_f32_e32 v155, v156, v157
	v_pk_fma_f32 v[122:123], v[98:99], v[60:61], v[122:123] op_sel:[1,0,0] op_sel_hi:[1,1,1]
	v_pk_fma_f32 v[120:121], v[98:99], v[62:63], v[120:121] op_sel:[1,0,0] op_sel_hi:[1,1,1]
	ds_read_b128 v[0:3], v154 offset:43008
	ds_read_b128 v[4:7], v154 offset:43024
	v_add_f32_e32 v158, v158, v159
	v_add_f32_dpp v155, v155, v155 quad_perm:[1,0,3,2] row_mask:0xf bank_mask:0xf bound_ctrl:1
	s_mov_b32 s6, 0x4040404
	s_mov_b32 s7, 0x4040404
	v_add_f32_dpp v158, v158, v158 quad_perm:[1,0,3,2] row_mask:0xf bank_mask:0xf bound_ctrl:1
	v_add_f32_dpp v155, v155, v155 quad_perm:[2,3,0,1] row_mask:0xf bank_mask:0xf bound_ctrl:1
	s_nop 0
	v_add_f32_dpp v158, v158, v158 quad_perm:[2,3,0,1] row_mask:0xf bank_mask:0xf bound_ctrl:1
	v_add_f32_dpp v156, v155, v155 row_half_mirror row_mask:0xf bank_mask:0xf bound_ctrl:1
	v_pk_fma_f32 v[126:127], v[156:157], v[72:73], v[126:127] op_sel_hi:[0,1,1]
	v_pk_fma_f32 v[124:125], v[156:157], v[74:75], v[124:125] op_sel_hi:[0,1,1]
	v_add_f32_dpp v158, v158, v158 row_half_mirror row_mask:0xf bank_mask:0xf bound_ctrl:1
	v_pk_fma_f32 v[122:123], v[156:157], v[76:77], v[122:123] op_sel_hi:[0,1,1]
	v_pk_fma_f32 v[120:121], v[156:157], v[78:79], v[120:121] op_sel_hi:[0,1,1]
	v_cndmask_b32_e64 v94, v94, v158, s[6:7]
	ds_read_b128 v[64:67], v154 offset:45312
	ds_read_b128 v[68:71], v154 offset:45328
	ds_read_b128 v[56:59], v154 offset:45056
	ds_read_b128 v[60:63], v154 offset:45072
	ds_read_b128 v[72:75], v154 offset:45568
	ds_read_b128 v[76:79], v154 offset:45584
	s_waitcnt lgkmcnt(6)
	v_pk_mul_f32 v[156:157], v[24:25], v[126:127]
	v_pk_mul_f32 v[90:91], v[28:29], v[122:123]
	v_pk_mul_f32 v[158:159], v[40:41], v[126:127]
	v_pk_fma_f32 v[156:157], v[124:125], v[26:27], v[156:157]
	v_pk_fma_f32 v[90:91], v[120:121], v[30:31], v[90:91]
	v_pk_fma_f32 v[158:159], v[124:125], v[42:43], v[158:159]
	v_pk_fma_f32 v[126:127], v[92:93], v[16:17], v[126:127] op_sel_hi:[0,1,1]
	v_pk_fma_f32 v[158:159], v[122:123], v[44:45], v[158:159]
	v_pk_fma_f32 v[124:125], v[92:93], v[18:19], v[124:125] op_sel_hi:[0,1,1]
	v_pk_add_f32 v[156:157], v[156:157], v[90:91]
	v_pk_fma_f32 v[158:159], v[120:121], v[46:47], v[158:159]
	v_add_f32_e32 v155, v156, v157
	v_pk_fma_f32 v[122:123], v[92:93], v[20:21], v[122:123] op_sel_hi:[0,1,1]
	v_pk_fma_f32 v[120:121], v[92:93], v[22:23], v[120:121] op_sel_hi:[0,1,1]
	ds_read_b128 v[40:43], v154 offset:44544
	ds_read_b128 v[44:47], v154 offset:44560
	v_add_f32_e32 v158, v158, v159
	v_add_f32_dpp v155, v155, v155 quad_perm:[1,0,3,2] row_mask:0xf bank_mask:0xf bound_ctrl:1
	s_mov_b32 s6, 0x8080808
	s_mov_b32 s7, 0x8080808
	v_add_f32_dpp v158, v158, v158 quad_perm:[1,0,3,2] row_mask:0xf bank_mask:0xf bound_ctrl:1
	v_add_f32_dpp v155, v155, v155 quad_perm:[2,3,0,1] row_mask:0xf bank_mask:0xf bound_ctrl:1
	s_nop 0
	v_add_f32_dpp v158, v158, v158 quad_perm:[2,3,0,1] row_mask:0xf bank_mask:0xf bound_ctrl:1
	v_add_f32_dpp v156, v155, v155 row_half_mirror row_mask:0xf bank_mask:0xf bound_ctrl:1
	v_pk_fma_f32 v[126:127], v[156:157], v[32:33], v[126:127] op_sel_hi:[0,1,1]
	v_pk_fma_f32 v[124:125], v[156:157], v[34:35], v[124:125] op_sel_hi:[0,1,1]
	v_add_f32_dpp v158, v158, v158 row_half_mirror row_mask:0xf bank_mask:0xf bound_ctrl:1
	v_pk_fma_f32 v[122:123], v[156:157], v[36:37], v[122:123] op_sel_hi:[0,1,1]
	v_pk_fma_f32 v[120:121], v[156:157], v[38:39], v[120:121] op_sel_hi:[0,1,1]
	v_cndmask_b32_e64 v94, v94, v158, s[6:7]
	ds_read_b128 v[24:27], v154 offset:46848
	ds_read_b128 v[28:31], v154 offset:46864
	ds_read_b128 v[16:19], v154 offset:46592
	ds_read_b128 v[20:23], v154 offset:46608
	ds_read_b128 v[32:35], v154 offset:47104
	ds_read_b128 v[36:39], v154 offset:47120
	ds_read2st64_b32 v[98:99], v153 offset0:185 offset1:191
	s_waitcnt lgkmcnt(7)
	v_pk_mul_f32 v[156:157], v[64:65], v[126:127]
	v_pk_mul_f32 v[90:91], v[68:69], v[122:123]
	v_pk_mul_f32 v[158:159], v[0:1], v[126:127]
	v_pk_fma_f32 v[156:157], v[124:125], v[66:67], v[156:157]
	v_pk_fma_f32 v[90:91], v[120:121], v[70:71], v[90:91]
	v_pk_fma_f32 v[158:159], v[124:125], v[2:3], v[158:159]
	v_pk_fma_f32 v[126:127], v[92:93], v[56:57], v[126:127] op_sel:[1,0,0] op_sel_hi:[1,1,1]
	v_pk_fma_f32 v[158:159], v[122:123], v[4:5], v[158:159]
	v_pk_fma_f32 v[124:125], v[92:93], v[58:59], v[124:125] op_sel:[1,0,0] op_sel_hi:[1,1,1]
	v_pk_add_f32 v[156:157], v[156:157], v[90:91]
	v_pk_fma_f32 v[158:159], v[120:121], v[6:7], v[158:159]
	v_add_f32_e32 v155, v156, v157
	v_pk_fma_f32 v[122:123], v[92:93], v[60:61], v[122:123] op_sel:[1,0,0] op_sel_hi:[1,1,1]
	v_pk_fma_f32 v[120:121], v[92:93], v[62:63], v[120:121] op_sel:[1,0,0] op_sel_hi:[1,1,1]
	ds_read_b128 v[0:3], v154 offset:46080
	ds_read_b128 v[4:7], v154 offset:46096
	v_add_f32_e32 v158, v158, v159
	v_add_f32_dpp v155, v155, v155 quad_perm:[1,0,3,2] row_mask:0xf bank_mask:0xf bound_ctrl:1
	s_mov_b32 s6, 0x10101010
	s_mov_b32 s7, 0x10101010
	v_add_f32_dpp v158, v158, v158 quad_perm:[1,0,3,2] row_mask:0xf bank_mask:0xf bound_ctrl:1
	v_add_f32_dpp v155, v155, v155 quad_perm:[2,3,0,1] row_mask:0xf bank_mask:0xf bound_ctrl:1
	s_nop 0
	v_add_f32_dpp v158, v158, v158 quad_perm:[2,3,0,1] row_mask:0xf bank_mask:0xf bound_ctrl:1
	v_add_f32_dpp v156, v155, v155 row_half_mirror row_mask:0xf bank_mask:0xf bound_ctrl:1
	v_pk_fma_f32 v[126:127], v[156:157], v[72:73], v[126:127] op_sel_hi:[0,1,1]
	v_pk_fma_f32 v[124:125], v[156:157], v[74:75], v[124:125] op_sel_hi:[0,1,1]
	v_add_f32_dpp v158, v158, v158 row_half_mirror row_mask:0xf bank_mask:0xf bound_ctrl:1
	v_pk_fma_f32 v[122:123], v[156:157], v[76:77], v[122:123] op_sel_hi:[0,1,1]
	v_pk_fma_f32 v[120:121], v[156:157], v[78:79], v[120:121] op_sel_hi:[0,1,1]
	v_cndmask_b32_e64 v94, v94, v158, s[6:7]
	ds_read_b128 v[64:67], v154 offset:48384
	ds_read_b128 v[68:71], v154 offset:48400
	ds_read_b128 v[56:59], v154 offset:48128
	ds_read_b128 v[60:63], v154 offset:48144
	ds_read_b128 v[72:75], v154 offset:48640
	ds_read_b128 v[76:79], v154 offset:48656
	ds_read_b128 v[48:51], v154 offset:47872
	ds_read_b128 v[52:55], v154 offset:47888
	s_waitcnt lgkmcnt(8)
; #define LAS __attribute__((address_space(3)))
; DI unsigned pack2(float lo, float hi) { f32x2 v = {lo, hi}; return __builtin_bit_cast(unsigned, __builtin_convertvector(v, bf16x2_t)); }
; DI void scan_item(PP p, int l, int item, LAS unsigned char* lds) {
;     ...
;     for (int c = 0; c < NCH; ++c) {
;         if (wid >= 4) { if (c + 1 < NCH) { fill(c + 1); if (c + 2 < NCH) gl(c + 2); } }
;         else {
;             const LAS float* sp = buf + ((c & 1) * T) * 384;
;             f32x4 Ar0, Ar1, Aw0, Aw1, Ak0, Ak1, Aa0, Aa1, Ab0, Ab1; float Avv;
;             f32x4 Br0, Br1, Bw0, Bw1, Bk0, Bk1, Ba0, Ba1, Bb0, Bb1; float Bvv;
;             SC_LD(A, sp);
;             const ptrdiff_t ystep = dir ? -512 : 512;
;             u16* Yl = Yp + (size_t)steprow(b, dir, c * T) * 512 + (ptrdiff_t)ks * ystep;
; #pragma nounroll
;             for (int st = 0; st < T; st += 2) {
;                 SC_LD(B, sp + (st + 1) * 384);
;                 SC_STEP(A, st);
;                 if (st + 2 < T) SC_LD(A, sp + (st + 2) * 384);
;                 SC_STEP(B, st + 1);
;                 if ((st & 6) == 6) {
;                     const LAS float* rp = ypl + (ks * 68 - lane) + (lane & ~7);
;                     const f32x4 q0 = *(const LAS f32x4*)rp, q1 = *(const LAS f32x4*)(rp + 4);
;                     Yl[(ptrdiff_t)(st - 6) * ystep] = (u16)(pack2(((q0[0] + q0[1]) + (q0[2] + q0[3])) + ((q1[0] + q1[1]) + (q1[2] + q1[3])), 0.f) & 0xffffu);
;                 }
	v_pk_mul_f32 v[156:157], v[24:25], v[126:127]
	v_pk_mul_f32 v[90:91], v[28:29], v[122:123]
	v_pk_mul_f32 v[158:159], v[40:41], v[126:127]
	v_pk_fma_f32 v[156:157], v[124:125], v[26:27], v[156:157]
	v_pk_fma_f32 v[90:91], v[120:121], v[30:31], v[90:91]
	v_pk_fma_f32 v[158:159], v[124:125], v[42:43], v[158:159]
	v_pk_fma_f32 v[126:127], v[98:99], v[16:17], v[126:127] op_sel_hi:[0,1,1]
	v_pk_fma_f32 v[158:159], v[122:123], v[44:45], v[158:159]
	v_pk_fma_f32 v[124:125], v[98:99], v[18:19], v[124:125] op_sel_hi:[0,1,1]
	v_pk_add_f32 v[156:157], v[156:157], v[90:91]
	v_pk_fma_f32 v[158:159], v[120:121], v[46:47], v[158:159]
	v_add_f32_e32 v155, v156, v157
	v_pk_fma_f32 v[122:123], v[98:99], v[20:21], v[122:123] op_sel_hi:[0,1,1]
	v_pk_fma_f32 v[120:121], v[98:99], v[22:23], v[120:121] op_sel_hi:[0,1,1]
	ds_read_b128 v[40:43], v154 offset:47616
	ds_read_b128 v[44:47], v154 offset:47632
	v_add_f32_e32 v158, v158, v159
	v_add_f32_dpp v155, v155, v155 quad_perm:[1,0,3,2] row_mask:0xf bank_mask:0xf bound_ctrl:1
	s_mov_b32 s6, 0x20202020
	s_mov_b32 s7, 0x20202020
	v_add_f32_dpp v158, v158, v158 quad_perm:[1,0,3,2] row_mask:0xf bank_mask:0xf bound_ctrl:1
	v_add_f32_dpp v155, v155, v155 quad_perm:[2,3,0,1] row_mask:0xf bank_mask:0xf bound_ctrl:1
	s_nop 0
	v_add_f32_dpp v158, v158, v158 quad_perm:[2,3,0,1] row_mask:0xf bank_mask:0xf bound_ctrl:1
	v_add_f32_dpp v156, v155, v155 row_half_mirror row_mask:0xf bank_mask:0xf bound_ctrl:1
	v_pk_fma_f32 v[126:127], v[156:157], v[32:33], v[126:127] op_sel_hi:[0,1,1]
	v_pk_fma_f32 v[124:125], v[156:157], v[34:35], v[124:125] op_sel_hi:[0,1,1]
	v_add_f32_dpp v158, v158, v158 row_half_mirror row_mask:0xf bank_mask:0xf bound_ctrl:1
	v_pk_fma_f32 v[122:123], v[156:157], v[36:37], v[122:123] op_sel_hi:[0,1,1]
	v_pk_fma_f32 v[120:121], v[156:157], v[38:39], v[120:121] op_sel_hi:[0,1,1]
	v_cndmask_b32_e64 v94, v94, v158, s[6:7]
	s_waitcnt lgkmcnt(0)
	v_pk_mul_f32 v[156:157], v[64:65], v[126:127]
	v_pk_mul_f32 v[90:91], v[68:69], v[122:123]
	v_pk_mul_f32 v[158:159], v[0:1], v[126:127]
	v_pk_fma_f32 v[156:157], v[124:125], v[66:67], v[156:157]
	v_pk_fma_f32 v[90:91], v[120:121], v[70:71], v[90:91]
	v_pk_fma_f32 v[158:159], v[124:125], v[2:3], v[158:159]
	v_pk_fma_f32 v[126:127], v[98:99], v[56:57], v[126:127] op_sel:[1,0,0] op_sel_hi:[1,1,1]
	v_pk_fma_f32 v[158:159], v[122:123], v[4:5], v[158:159]
	v_pk_fma_f32 v[124:125], v[98:99], v[58:59], v[124:125] op_sel:[1,0,0] op_sel_hi:[1,1,1]
	v_pk_add_f32 v[156:157], v[156:157], v[90:91]
	v_pk_fma_f32 v[158:159], v[120:121], v[6:7], v[158:159]
	v_add_f32_e32 v155, v156, v157
	v_pk_fma_f32 v[122:123], v[98:99], v[60:61], v[122:123] op_sel:[1,0,0] op_sel_hi:[1,1,1]
	v_pk_fma_f32 v[120:121], v[98:99], v[62:63], v[120:121] op_sel:[1,0,0] op_sel_hi:[1,1,1]
	v_add_f32_e32 v158, v158, v159
	v_add_f32_dpp v155, v155, v155 quad_perm:[1,0,3,2] row_mask:0xf bank_mask:0xf bound_ctrl:1
	s_mov_b32 s6, 0x40404040
	s_mov_b32 s7, 0x40404040
	v_add_f32_dpp v158, v158, v158 quad_perm:[1,0,3,2] row_mask:0xf bank_mask:0xf bound_ctrl:1
	v_add_f32_dpp v155, v155, v155 quad_perm:[2,3,0,1] row_mask:0xf bank_mask:0xf bound_ctrl:1
	s_nop 0
	v_add_f32_dpp v158, v158, v158 quad_perm:[2,3,0,1] row_mask:0xf bank_mask:0xf bound_ctrl:1
	v_add_f32_dpp v156, v155, v155 row_half_mirror row_mask:0xf bank_mask:0xf bound_ctrl:1
	v_pk_fma_f32 v[126:127], v[156:157], v[72:73], v[126:127] op_sel_hi:[0,1,1]
	v_pk_fma_f32 v[124:125], v[156:157], v[74:75], v[124:125] op_sel_hi:[0,1,1]
	v_add_f32_dpp v158, v158, v158 row_half_mirror row_mask:0xf bank_mask:0xf bound_ctrl:1
	v_pk_fma_f32 v[122:123], v[156:157], v[76:77], v[122:123] op_sel_hi:[0,1,1]
	v_pk_fma_f32 v[120:121], v[156:157], v[78:79], v[120:121] op_sel_hi:[0,1,1]
	v_cndmask_b32_e64 v94, v94, v158, s[6:7]
	v_pk_mul_f32 v[158:159], v[40:41], v[126:127]
	s_nop 0
	v_pk_fma_f32 v[158:159], v[124:125], v[42:43], v[158:159]
	s_nop 0
	v_pk_fma_f32 v[158:159], v[122:123], v[44:45], v[158:159]
	s_nop 0
	v_pk_fma_f32 v[158:159], v[120:121], v[46:47], v[158:159]
	s_nop 0
	v_add_f32_e32 v158, v158, v159
	s_mov_b32 s6, 0x80808080
	s_mov_b32 s7, 0x80808080
	v_add_f32_dpp v158, v158, v158 quad_perm:[1,0,3,2] row_mask:0xf bank_mask:0xf bound_ctrl:1
	s_nop 1
	v_add_f32_dpp v158, v158, v158 quad_perm:[2,3,0,1] row_mask:0xf bank_mask:0xf bound_ctrl:1
	s_nop 1
	v_add_f32_dpp v158, v158, v158 row_half_mirror row_mask:0xf bank_mask:0xf bound_ctrl:1
	v_pk_mul_f32 v[126:127], v[48:49], v[126:127]
	v_pk_mul_f32 v[124:125], v[50:51], v[124:125]
	v_pk_mul_f32 v[122:123], v[52:53], v[122:123]
	v_pk_mul_f32 v[120:121], v[54:55], v[120:121]
	v_cndmask_b32_e64 v94, v94, v158, s[6:7]
	v_cvt_pk_bf16_f32 v82, v94, v94
	global_store_short v[118:119], v82, off
	s_setprio 0
